# previous combined version + accumulator zeroing folded into a peeled first K half-iteration (srcC=0 on first-touch MFMAs) in 5 GEMM K-loops
# speedup vs baseline: 1.0100x; 1.0004x over previous
; template <class Epi, class Sched, bool ALIGN_EPI = false, bool SP2 = false, bool F8 = false>
; __device__ __forceinline__ void gemm_phase(PG8_LAS unsigned char* lds, const int K, const Sched& S, const Epi& E, const int wave) {
;     ...
; #pragma unroll
;         for (int a = 0; a < 2; ++a)
; #pragma unroll
;             for (int b = 0; b < 2; ++b)
; #pragma unroll
;                 for (int m = 0; m < 4; ++m)
; #pragma unroll
;                     for (int n = 0; n < 2; ++n) acc[a][b][m][n] = (f32x4){0.f, 0.f, 0.f, 0.f};
;         cur = nxt; cA = nA; cB = nB; ++ui;
.LBB0_161:
	s_mov_b32 s11, s45
	s_mov_b32 s12, s82
	s_mov_b32 s10, s84
	s_mov_b64 s[14:15], s[86:87]
	s_mov_b64 s[36:37], s[88:89]
	s_mov_b32 s49, s42

; #define PG8_STAGE(bufoff, gbase, voff) do { _Pragma("unroll") for (int _i = 0; _i < 2; ++_i) \
;         __builtin_amdgcn_global_load_lds((const unsigned*)((const char*)(gbase) + (voff)[_i]), (PG8_LAS unsigned*)(lds + (bufoff) + ldsw + _i * 8192), 16, 0, 0); } while (0)
; #define PG8_LDA(dst, b, h) do { _Pragma("unroll") for (int m = 0; m < 4; ++m) _Pragma("unroll") for (int k = 0; k < 2; ++k) dst[m][k] = *(const PG8_LAS bf16x8*)(lds + PG8_SA(b, h) + aoff + m * 2048 + k * 1024); } while (0)
; #define PG8_LDB(dst, b, h) do { _Pragma("unroll") for (int n = 0; n < 2; ++n) _Pragma("unroll") for (int k = 0; k < 2; ++k) dst[n][k] = *(const PG8_LAS bf16x8*)(lds + PG8_SB(b, h) + boff + n * 2048 + k * 1024); } while (0)
; #define PG8_WAIT_V(n) asm volatile("s_waitcnt vmcnt(" #n ")" ::: "memory")
; #define PG8_WAIT_L(n) asm volatile("s_waitcnt lgkmcnt(" #n ")" ::: "memory")
; #define PG8_BAR __builtin_amdgcn_s_barrier()
; #define PG8_SCHED __builtin_amdgcn_sched_barrier(0)
; template <class Epi, class Sched, bool ALIGN_EPI = false, bool SP2 = false, bool F8 = false>
; __device__ __forceinline__ void gemm_phase(PG8_LAS unsigned char* lds, const int K, const Sched& S, const Epi& E, const int wave) {
;     ...
;         const bool has_next = S.next(ui + 1, nxt);
;         const char* nA = has_next ? nxt.a : cA; const char* nB = has_next ? nxt.b : cB;
;         const int nt = cur.nt;
;         for (int t = 0; t < nt; t += 2) {
;             const bool last = (t == nt - 2);
;             const char* a1 = cA + (size_t)(t + 1) * kstep;
;             const char* a2 = last ? nA : cA + (size_t)(t + 2) * kstep; const char* b2 = last ? nB : cB + (size_t)(t + 2) * kstep;
;             const char* a3 = a2 + kstep; const char* b3 = b2 + kstep;
;             asm volatile("" : "+s"(a1), "+s"(a2), "+s"(b2), "+s"(a3), "+s"(b3));
;     ...
;             PG8_LDB(B0, 0, 0); PG8_LDB(B1, 0, 1); PG8_SCHED; PG8_LDA(At, 0, 0); PG8_STAGE(PG8_SA(1, 1), a1 + hstep, voffA);
;             PG8_WAIT_V(8); PG8_WAIT_L(0); PG8_BAR; PG8_MMA(0, 0, At, B0); PG8_MMA(0, 1, At, B1); PG8_BAR; PG8_SCHED;
.LBB0_185:
	s_xor_b64 s[90:91], s[92:93], -1
	s_and_b64 s[0:1], s[92:93], exec
	s_cselect_b32 s83, s87, s15
	s_cselect_b32 s85, s86, s14
	s_cselect_b32 s96, s89, s37
	s_cselect_b32 s97, s88, s36
	s_mov_b32 vcc_lo, -2
	s_mov_b64 s[0:1], 0x100
	s_add_u32 s6, s14, s0
	s_addc_u32 s7, s15, s1
	s_add_u32 s64, s6, 0xffffff80
	s_addc_u32 s65, s7, -1
	s_add_u32 s76, s36, s0
	s_addc_u32 s77, s37, s1
	s_cmp_eq_u32 vcc_lo, 60
	s_cselect_b32 s94, s85, s6
	s_cselect_b32 s95, s83, s7
	s_cselect_b32 s7, s96, s77
	s_cselect_b32 s6, s97, s76
	s_add_u32 s78, s94, 0x80
	s_addc_u32 s79, s95, 0
	s_add_u32 s76, s6, 0x80
	s_addc_u32 s77, s7, 0
	v_add_u32_e32 v140, s47, v245
	v_add_u32_e32 v156, s41, v245
	ds_read_b128 v[128:131], v140
	ds_read_b128 v[132:135], v140 offset:1024
	ds_read_b128 v[136:139], v140 offset:2048
	ds_read_b128 v[140:143], v140 offset:3072
	ds_read_b128 v[144:147], v156
	ds_read_b128 v[148:151], v156 offset:1024
	ds_read_b128 v[152:155], v156 offset:2048
	ds_read_b128 v[156:159], v156 offset:3072
	s_add_u32 s64, s64, 0x100000
	s_addc_u32 s65, s65, 0
	v_lshl_add_u64 v[240:241], s[64:65], 0, v[192:193]
	s_add_i32 m0, s13, 0xc000
	ds_read_b128 v[160:163], v248
	ds_read_b128 v[164:167], v248 offset:1024
	ds_read_b128 v[168:171], v248 offset:2048
	ds_read_b128 v[172:175], v248 offset:3072
	ds_read_b128 v[176:179], v248 offset:4096
	ds_read_b128 v[180:183], v248 offset:5120
	ds_read_b128 v[184:187], v248 offset:6144
	ds_read_b128 v[188:191], v248 offset:7168
	global_load_lds_dwordx4 v[240:241], off
	v_lshl_add_u64 v[240:241], s[64:65], 0, v[196:197]
	s_add_i32 m0, s13, 0xe000
	s_nop 0
	global_load_lds_dwordx4 v[240:241], off
	s_waitcnt vmcnt(8)
	s_waitcnt lgkmcnt(0)
	s_setprio 1
	s_barrier
	v_mfma_f32_16x16x32_bf16 v[124:127], v[128:131], v[160:163], 0
	v_mfma_f32_16x16x32_bf16 v[120:123], v[136:139], v[160:163], 0
	v_mfma_f32_16x16x32_bf16 v[116:119], v[128:131], v[168:171], 0
	v_mfma_f32_16x16x32_bf16 v[112:115], v[136:139], v[168:171], 0
	v_mfma_f32_16x16x32_bf16 v[108:111], v[128:131], v[176:179], 0
	v_mfma_f32_16x16x32_bf16 v[104:107], v[136:139], v[176:179], 0
	v_mfma_f32_16x16x32_bf16 v[100:103], v[128:131], v[184:187], 0
	v_mfma_f32_16x16x32_bf16 v[96:99], v[136:139], v[184:187], 0
	v_mfma_f32_16x16x32_bf16 v[124:127], v[132:135], v[164:167], v[124:127]
	v_mfma_f32_16x16x32_bf16 v[120:123], v[140:143], v[164:167], v[120:123]
	v_mfma_f32_16x16x32_bf16 v[116:119], v[132:135], v[172:175], v[116:119]
	v_mfma_f32_16x16x32_bf16 v[112:115], v[140:143], v[172:175], v[112:115]
	v_mfma_f32_16x16x32_bf16 v[108:111], v[132:135], v[180:183], v[108:111]
	v_mfma_f32_16x16x32_bf16 v[104:107], v[140:143], v[180:183], v[104:107]
	v_mfma_f32_16x16x32_bf16 v[100:103], v[132:135], v[188:191], v[100:103]
	v_mfma_f32_16x16x32_bf16 v[96:99], v[140:143], v[188:191], v[96:99]
	v_mfma_f32_16x16x32_bf16 v[92:95], v[144:147], v[160:163], 0
	v_mfma_f32_16x16x32_bf16 v[88:91], v[152:155], v[160:163], 0
	v_mfma_f32_16x16x32_bf16 v[84:87], v[144:147], v[168:171], 0
	v_mfma_f32_16x16x32_bf16 v[80:83], v[152:155], v[168:171], 0
	v_mfma_f32_16x16x32_bf16 v[76:79], v[144:147], v[176:179], 0
	v_mfma_f32_16x16x32_bf16 v[72:75], v[152:155], v[176:179], 0
	v_mfma_f32_16x16x32_bf16 v[68:71], v[144:147], v[184:187], 0
	v_mfma_f32_16x16x32_bf16 v[64:67], v[152:155], v[184:187], 0
	v_mfma_f32_16x16x32_bf16 v[92:95], v[148:151], v[164:167], v[92:95]
	v_mfma_f32_16x16x32_bf16 v[88:91], v[156:159], v[164:167], v[88:91]
	v_mfma_f32_16x16x32_bf16 v[84:87], v[148:151], v[172:175], v[84:87]
	v_mfma_f32_16x16x32_bf16 v[80:83], v[156:159], v[172:175], v[80:83]
	v_mfma_f32_16x16x32_bf16 v[76:79], v[148:151], v[180:183], v[76:79]
	v_mfma_f32_16x16x32_bf16 v[72:75], v[156:159], v[180:183], v[72:75]
	v_mfma_f32_16x16x32_bf16 v[68:71], v[148:151], v[188:191], v[68:71]
	v_mfma_f32_16x16x32_bf16 v[64:67], v[156:159], v[188:191], v[64:67]
	s_barrier
; #define PG8_STAGE(bufoff, gbase, voff) do { _Pragma("unroll") for (int _i = 0; _i < 2; ++_i) \
;         __builtin_amdgcn_global_load_lds((const unsigned*)((const char*)(gbase) + (voff)[_i]), (PG8_LAS unsigned*)(lds + (bufoff) + ldsw + _i * 8192), 16, 0, 0); } while (0)
; #define PG8_LDA(dst, b, h) do { _Pragma("unroll") for (int m = 0; m < 4; ++m) _Pragma("unroll") for (int k = 0; k < 2; ++k) dst[m][k] = *(const PG8_LAS bf16x8*)(lds + PG8_SA(b, h) + aoff + m * 2048 + k * 1024); } while (0)
; #define PG8_WAIT_V(n) asm volatile("s_waitcnt vmcnt(" #n ")" ::: "memory")
; #define PG8_WAIT_L(n) asm volatile("s_waitcnt lgkmcnt(" #n ")" ::: "memory")
; #define PG8_BAR __builtin_amdgcn_s_barrier()
; #define PG8_SCHED __builtin_amdgcn_sched_barrier(0)
; template <class Epi, class Sched, bool ALIGN_EPI = false, bool SP2 = false, bool F8 = false>
; __device__ __forceinline__ void gemm_phase(PG8_LAS unsigned char* lds, const int K, const Sched& S, const Epi& E, const int wave) {
;     ...
;             PG8_LDA(At, 0, 1); PG8_STAGE(PG8_SB(0, 0), b2, voffB); PG8_STAGE(PG8_SB(0, 1), b2 + hstep, voffB); PG8_STAGE(PG8_SA(0, 0), a2, voffA);
;             PG8_WAIT_V(8); PG8_WAIT_L(0); PG8_BAR; PG8_MMA(1, 0, At, B0); PG8_MMA(1, 1, At, B1); PG8_BAR; PG8_SCHED;
	s_setprio 0
	s_add_i32 s64, s47, s74
	v_lshl_add_u64 v[240:241], s[6:7], 0, v[194:195]
	s_mov_b32 m0, s64
	ds_read_b128 v[160:163], v248 offset:16384
	ds_read_b128 v[164:167], v248 offset:17408
	ds_read_b128 v[168:171], v248 offset:18432
	ds_read_b128 v[172:175], v248 offset:19456
	ds_read_b128 v[176:179], v248 offset:20480
	ds_read_b128 v[180:183], v248 offset:21504
	ds_read_b128 v[184:187], v248 offset:22528
	ds_read_b128 v[188:191], v248 offset:23552
	global_load_lds_dwordx4 v[240:241], off
	s_add_i32 m0, s64, 0x2000
	v_lshl_add_u64 v[240:241], s[6:7], 0, v[198:199]
	s_add_u32 s6, s6, 0x100000
	s_addc_u32 s7, s7, 0
	s_add_i32 s64, s41, s74
	global_load_lds_dwordx4 v[240:241], off
	v_lshl_add_u64 v[240:241], s[6:7], 0, v[194:195]
	s_mov_b32 m0, s64
	s_nop 0
	global_load_lds_dwordx4 v[240:241], off
	v_lshl_add_u64 v[240:241], s[6:7], 0, v[198:199]
	s_add_i32 m0, s64, 0x2000
	s_nop 0
	global_load_lds_dwordx4 v[240:241], off
	v_lshl_add_u64 v[240:241], s[94:95], 0, v[192:193]
	s_mov_b32 m0, s13
	s_nop 0
	global_load_lds_dwordx4 v[240:241], off
	v_lshl_add_u64 v[240:241], s[94:95], 0, v[196:197]
	s_mov_b32 m0, s51
	s_nop 0
	global_load_lds_dwordx4 v[240:241], off
	s_waitcnt vmcnt(8)
	s_waitcnt lgkmcnt(0)
	s_setprio 1
	s_barrier
	v_mfma_f32_16x16x32_bf16 v[60:63], v[128:131], v[160:163], 0
	v_mfma_f32_16x16x32_bf16 v[56:59], v[136:139], v[160:163], 0
	v_mfma_f32_16x16x32_bf16 v[52:55], v[128:131], v[168:171], 0
	v_mfma_f32_16x16x32_bf16 v[48:51], v[136:139], v[168:171], 0
	v_mfma_f32_16x16x32_bf16 v[44:47], v[128:131], v[176:179], 0
	v_mfma_f32_16x16x32_bf16 v[40:43], v[136:139], v[176:179], 0
	v_mfma_f32_16x16x32_bf16 v[36:39], v[128:131], v[184:187], 0
	v_mfma_f32_16x16x32_bf16 v[32:35], v[136:139], v[184:187], 0
	v_mfma_f32_16x16x32_bf16 v[60:63], v[132:135], v[164:167], v[60:63]
	v_mfma_f32_16x16x32_bf16 v[56:59], v[140:143], v[164:167], v[56:59]
	v_mfma_f32_16x16x32_bf16 v[52:55], v[132:135], v[172:175], v[52:55]
	v_mfma_f32_16x16x32_bf16 v[48:51], v[140:143], v[172:175], v[48:51]
	v_mfma_f32_16x16x32_bf16 v[44:47], v[132:135], v[180:183], v[44:47]
	v_mfma_f32_16x16x32_bf16 v[40:43], v[140:143], v[180:183], v[40:43]
	v_mfma_f32_16x16x32_bf16 v[36:39], v[132:135], v[188:191], v[36:39]
	v_mfma_f32_16x16x32_bf16 v[32:35], v[140:143], v[188:191], v[32:35]
	v_mfma_f32_16x16x32_bf16 v[28:31], v[144:147], v[160:163], 0
	v_mfma_f32_16x16x32_bf16 v[24:27], v[152:155], v[160:163], 0
	v_mfma_f32_16x16x32_bf16 v[20:23], v[144:147], v[168:171], 0
	v_mfma_f32_16x16x32_bf16 v[16:19], v[152:155], v[168:171], 0
	v_mfma_f32_16x16x32_bf16 v[12:15], v[144:147], v[176:179], 0
	v_mfma_f32_16x16x32_bf16 v[8:11], v[152:155], v[176:179], 0
	v_mfma_f32_16x16x32_bf16 v[4:7], v[144:147], v[184:187], 0
	v_mfma_f32_16x16x32_bf16 v[0:3], v[152:155], v[184:187], 0
	v_mfma_f32_16x16x32_bf16 v[28:31], v[148:151], v[164:167], v[28:31]
	v_mfma_f32_16x16x32_bf16 v[24:27], v[156:159], v[164:167], v[24:27]
	v_mfma_f32_16x16x32_bf16 v[20:23], v[148:151], v[172:175], v[20:23]
	v_mfma_f32_16x16x32_bf16 v[16:19], v[156:159], v[172:175], v[16:19]
	v_mfma_f32_16x16x32_bf16 v[12:15], v[148:151], v[180:183], v[12:15]
	v_mfma_f32_16x16x32_bf16 v[8:11], v[156:159], v[180:183], v[8:11]
	v_mfma_f32_16x16x32_bf16 v[4:7], v[148:151], v[188:191], v[4:7]
	v_mfma_f32_16x16x32_bf16 v[0:3], v[156:159], v[188:191], v[0:3]
	s_barrier
	s_branch .Lmid_k186

; #define PG8_STAGE(bufoff, gbase, voff) do { _Pragma("unroll") for (int _i = 0; _i < 2; ++_i) \
;         __builtin_amdgcn_global_load_lds((const unsigned*)((const char*)(gbase) + (voff)[_i]), (PG8_LAS unsigned*)(lds + (bufoff) + ldsw + _i * 8192), 16, 0, 0); } while (0)
; #define PG8_LDA(dst, b, h) do { _Pragma("unroll") for (int m = 0; m < 4; ++m) _Pragma("unroll") for (int k = 0; k < 2; ++k) dst[m][k] = *(const PG8_LAS bf16x8*)(lds + PG8_SA(b, h) + aoff + m * 2048 + k * 1024); } while (0)
; #define PG8_LDB(dst, b, h) do { _Pragma("unroll") for (int n = 0; n < 2; ++n) _Pragma("unroll") for (int k = 0; k < 2; ++k) dst[n][k] = *(const PG8_LAS bf16x8*)(lds + PG8_SB(b, h) + boff + n * 2048 + k * 1024); } while (0)
; #define PG8_WAIT_V(n) asm volatile("s_waitcnt vmcnt(" #n ")" ::: "memory")
; #define PG8_WAIT_L(n) asm volatile("s_waitcnt lgkmcnt(" #n ")" ::: "memory")
; #define PG8_BAR __builtin_amdgcn_s_barrier()
; #define PG8_SCHED __builtin_amdgcn_sched_barrier(0)
; template <class Epi, class Sched, bool ALIGN_EPI = false, bool SP2 = false, bool F8 = false>
; __device__ __forceinline__ void gemm_phase(PG8_LAS unsigned char* lds, const int K, const Sched& S, const Epi& E, const int wave) {
;     ...
;             PG8_LDB(B0, 1, 0); PG8_LDB(B1, 1, 1); PG8_SCHED; PG8_LDA(At, 1, 0); PG8_STAGE(PG8_SA(0, 1), a2 + hstep, voffA);
;             PG8_WAIT_V(8); PG8_WAIT_L(0); PG8_BAR; PG8_MMA(0, 0, At, B0); PG8_MMA(0, 1, At, B1); PG8_BAR; PG8_SCHED;
.Lmid_k186:
	s_setprio 0
	s_add_i32 s64, 0, 0x18000
	s_add_i32 s65, 0, 0x1c000
	v_add_u32_e32 v140, s64, v245
	v_add_u32_e32 v156, s65, v245
	ds_read_b128 v[128:131], v140
	ds_read_b128 v[132:135], v140 offset:1024
	ds_read_b128 v[136:139], v140 offset:2048
	ds_read_b128 v[140:143], v140 offset:3072
	ds_read_b128 v[144:147], v156
	ds_read_b128 v[148:151], v156 offset:1024
	ds_read_b128 v[152:155], v156 offset:2048
	ds_read_b128 v[156:159], v156 offset:3072
	s_add_u32 s6, s94, 0x100000
	s_addc_u32 s7, s95, 0
	s_mov_b32 m0, s75
	v_lshl_add_u64 v[240:241], s[6:7], 0, v[192:193]
	ds_read_b128 v[160:163], v248 offset:32768
	ds_read_b128 v[164:167], v248 offset:33792
	ds_read_b128 v[168:171], v248 offset:34816
	ds_read_b128 v[172:175], v248 offset:35840
	ds_read_b128 v[176:179], v248 offset:36864
	ds_read_b128 v[180:183], v248 offset:37888
	ds_read_b128 v[184:187], v248 offset:38912
	ds_read_b128 v[188:191], v248 offset:39936
	global_load_lds_dwordx4 v[240:241], off
	v_lshl_add_u64 v[240:241], s[6:7], 0, v[196:197]
	s_mov_b32 m0, s48
	s_nop 0
	global_load_lds_dwordx4 v[240:241], off
	s_waitcnt vmcnt(8)
	s_waitcnt lgkmcnt(0)
	s_setprio 1
	s_barrier
	v_mfma_f32_16x16x32_bf16 v[124:127], v[128:131], v[160:163], v[124:127]
	v_mfma_f32_16x16x32_bf16 v[120:123], v[136:139], v[160:163], v[120:123]
	v_mfma_f32_16x16x32_bf16 v[116:119], v[128:131], v[168:171], v[116:119]
	v_mfma_f32_16x16x32_bf16 v[112:115], v[136:139], v[168:171], v[112:115]
	v_mfma_f32_16x16x32_bf16 v[108:111], v[128:131], v[176:179], v[108:111]
	v_mfma_f32_16x16x32_bf16 v[104:107], v[136:139], v[176:179], v[104:107]
	v_mfma_f32_16x16x32_bf16 v[100:103], v[128:131], v[184:187], v[100:103]
	v_mfma_f32_16x16x32_bf16 v[96:99], v[136:139], v[184:187], v[96:99]
	v_mfma_f32_16x16x32_bf16 v[124:127], v[132:135], v[164:167], v[124:127]
	v_mfma_f32_16x16x32_bf16 v[120:123], v[140:143], v[164:167], v[120:123]
	v_mfma_f32_16x16x32_bf16 v[116:119], v[132:135], v[172:175], v[116:119]
	v_mfma_f32_16x16x32_bf16 v[112:115], v[140:143], v[172:175], v[112:115]
	v_mfma_f32_16x16x32_bf16 v[108:111], v[132:135], v[180:183], v[108:111]
	v_mfma_f32_16x16x32_bf16 v[104:107], v[140:143], v[180:183], v[104:107]
	v_mfma_f32_16x16x32_bf16 v[100:103], v[132:135], v[188:191], v[100:103]
	v_mfma_f32_16x16x32_bf16 v[96:99], v[140:143], v[188:191], v[96:99]
	v_mfma_f32_16x16x32_bf16 v[92:95], v[144:147], v[160:163], v[92:95]
	v_mfma_f32_16x16x32_bf16 v[88:91], v[152:155], v[160:163], v[88:91]
	v_mfma_f32_16x16x32_bf16 v[84:87], v[144:147], v[168:171], v[84:87]
	v_mfma_f32_16x16x32_bf16 v[80:83], v[152:155], v[168:171], v[80:83]
	v_mfma_f32_16x16x32_bf16 v[76:79], v[144:147], v[176:179], v[76:79]
	v_mfma_f32_16x16x32_bf16 v[72:75], v[152:155], v[176:179], v[72:75]
	v_mfma_f32_16x16x32_bf16 v[68:71], v[144:147], v[184:187], v[68:71]
	v_mfma_f32_16x16x32_bf16 v[64:67], v[152:155], v[184:187], v[64:67]
	v_mfma_f32_16x16x32_bf16 v[92:95], v[148:151], v[164:167], v[92:95]
	v_mfma_f32_16x16x32_bf16 v[88:91], v[156:159], v[164:167], v[88:91]
	v_mfma_f32_16x16x32_bf16 v[84:87], v[148:151], v[172:175], v[84:87]
	v_mfma_f32_16x16x32_bf16 v[80:83], v[156:159], v[172:175], v[80:83]
	v_mfma_f32_16x16x32_bf16 v[76:79], v[148:151], v[180:183], v[76:79]
	v_mfma_f32_16x16x32_bf16 v[72:75], v[156:159], v[180:183], v[72:75]
	v_mfma_f32_16x16x32_bf16 v[68:71], v[148:151], v[188:191], v[68:71]
	v_mfma_f32_16x16x32_bf16 v[64:67], v[156:159], v[188:191], v[64:67]
	s_barrier
; #define PG8_STAGE(bufoff, gbase, voff) do { _Pragma("unroll") for (int _i = 0; _i < 2; ++_i) \
;         __builtin_amdgcn_global_load_lds((const unsigned*)((const char*)(gbase) + (voff)[_i]), (PG8_LAS unsigned*)(lds + (bufoff) + ldsw + _i * 8192), 16, 0, 0); } while (0)
; #define PG8_LDA(dst, b, h) do { _Pragma("unroll") for (int m = 0; m < 4; ++m) _Pragma("unroll") for (int k = 0; k < 2; ++k) dst[m][k] = *(const PG8_LAS bf16x8*)(lds + PG8_SA(b, h) + aoff + m * 2048 + k * 1024); } while (0)
; #define PG8_WAIT_V(n) asm volatile("s_waitcnt vmcnt(" #n ")" ::: "memory")
; #define PG8_WAIT_L(n) asm volatile("s_waitcnt lgkmcnt(" #n ")" ::: "memory")
; #define PG8_BAR __builtin_amdgcn_s_barrier()
; #define PG8_SCHED __builtin_amdgcn_sched_barrier(0)
; template <class Epi, class Sched, bool ALIGN_EPI = false, bool SP2 = false, bool F8 = false>
; __device__ __forceinline__ void gemm_phase(PG8_LAS unsigned char* lds, const int K, const Sched& S, const Epi& E, const int wave) {
;     ...
;             PG8_LDA(At, 1, 1); PG8_STAGE(PG8_SB(1, 0), b3, voffB); PG8_STAGE(PG8_SB(1, 1), b3 + hstep, voffB); PG8_STAGE(PG8_SA(1, 0), a3, voffA);
;             PG8_WAIT_V(8); PG8_WAIT_L(0); PG8_BAR; PG8_MMA(1, 0, At, B0); PG8_MMA(1, 1, At, B1); PG8_BAR; PG8_SCHED;
;     ...
;         }
;         if constexpr (ALIGN_EPI) { if (wr == 0) PG8_BAR; }
	s_setprio 0
	s_add_i32 s6, s64, s74
	v_lshl_add_u64 v[240:241], s[76:77], 0, v[194:195]
	s_mov_b32 m0, s6
	ds_read_b128 v[160:163], v248 offset:49152
	ds_read_b128 v[164:167], v248 offset:50176
	ds_read_b128 v[168:171], v248 offset:51200
	ds_read_b128 v[172:175], v248 offset:52224
	ds_read_b128 v[176:179], v248 offset:53248
	ds_read_b128 v[180:183], v248 offset:54272
	ds_read_b128 v[184:187], v248 offset:55296
	ds_read_b128 v[188:191], v248 offset:56320
	global_load_lds_dwordx4 v[240:241], off
	s_add_i32 m0, s6, 0x2000
	s_add_u32 s6, s76, 0x100000
	v_lshl_add_u64 v[240:241], s[76:77], 0, v[198:199]
	s_addc_u32 s7, s77, 0
	s_add_i32 s64, s65, s74
	global_load_lds_dwordx4 v[240:241], off
	v_lshl_add_u64 v[240:241], s[6:7], 0, v[194:195]
	s_mov_b32 m0, s64
	s_nop 0
	global_load_lds_dwordx4 v[240:241], off
	v_lshl_add_u64 v[240:241], s[6:7], 0, v[198:199]
	s_add_i32 m0, s64, 0x2000
	s_nop 0
	global_load_lds_dwordx4 v[240:241], off
	v_lshl_add_u64 v[240:241], s[78:79], 0, v[192:193]
	s_mov_b32 m0, s43
	s_nop 0
	global_load_lds_dwordx4 v[240:241], off
	v_lshl_add_u64 v[240:241], s[78:79], 0, v[196:197]
	s_mov_b32 m0, s44
	s_nop 0
	global_load_lds_dwordx4 v[240:241], off
	s_waitcnt vmcnt(8)
	s_waitcnt lgkmcnt(0)
	s_setprio 1
	s_barrier
	v_mfma_f32_16x16x32_bf16 v[60:63], v[128:131], v[160:163], v[60:63]
	v_mfma_f32_16x16x32_bf16 v[56:59], v[136:139], v[160:163], v[56:59]
	v_mfma_f32_16x16x32_bf16 v[52:55], v[128:131], v[168:171], v[52:55]
	v_mfma_f32_16x16x32_bf16 v[48:51], v[136:139], v[168:171], v[48:51]
	v_mfma_f32_16x16x32_bf16 v[44:47], v[128:131], v[176:179], v[44:47]
	v_mfma_f32_16x16x32_bf16 v[40:43], v[136:139], v[176:179], v[40:43]
	v_mfma_f32_16x16x32_bf16 v[36:39], v[128:131], v[184:187], v[36:39]
	v_mfma_f32_16x16x32_bf16 v[32:35], v[136:139], v[184:187], v[32:35]
	v_mfma_f32_16x16x32_bf16 v[60:63], v[132:135], v[164:167], v[60:63]
	v_mfma_f32_16x16x32_bf16 v[56:59], v[140:143], v[164:167], v[56:59]
	v_mfma_f32_16x16x32_bf16 v[52:55], v[132:135], v[172:175], v[52:55]
	v_mfma_f32_16x16x32_bf16 v[48:51], v[140:143], v[172:175], v[48:51]
	v_mfma_f32_16x16x32_bf16 v[44:47], v[132:135], v[180:183], v[44:47]
	v_mfma_f32_16x16x32_bf16 v[40:43], v[140:143], v[180:183], v[40:43]
	v_mfma_f32_16x16x32_bf16 v[36:39], v[132:135], v[188:191], v[36:39]
	v_mfma_f32_16x16x32_bf16 v[32:35], v[140:143], v[188:191], v[32:35]
	v_mfma_f32_16x16x32_bf16 v[28:31], v[144:147], v[160:163], v[28:31]
	v_mfma_f32_16x16x32_bf16 v[24:27], v[152:155], v[160:163], v[24:27]
	v_mfma_f32_16x16x32_bf16 v[20:23], v[144:147], v[168:171], v[20:23]
	v_mfma_f32_16x16x32_bf16 v[16:19], v[152:155], v[168:171], v[16:19]
	v_mfma_f32_16x16x32_bf16 v[12:15], v[144:147], v[176:179], v[12:15]
	v_mfma_f32_16x16x32_bf16 v[8:11], v[152:155], v[176:179], v[8:11]
	v_mfma_f32_16x16x32_bf16 v[4:7], v[144:147], v[184:187], v[4:7]
	v_mfma_f32_16x16x32_bf16 v[0:3], v[152:155], v[184:187], v[0:3]
	v_mfma_f32_16x16x32_bf16 v[28:31], v[148:151], v[164:167], v[28:31]
	v_mfma_f32_16x16x32_bf16 v[24:27], v[156:159], v[164:167], v[24:27]
	v_mfma_f32_16x16x32_bf16 v[20:23], v[148:151], v[172:175], v[20:23]
	v_mfma_f32_16x16x32_bf16 v[16:19], v[156:159], v[172:175], v[16:19]
	v_mfma_f32_16x16x32_bf16 v[12:15], v[148:151], v[180:183], v[12:15]
	v_mfma_f32_16x16x32_bf16 v[8:11], v[156:159], v[180:183], v[8:11]
	v_mfma_f32_16x16x32_bf16 v[4:7], v[148:151], v[188:191], v[4:7]
	v_mfma_f32_16x16x32_bf16 v[0:3], v[156:159], v[188:191], v[0:3]
	s_barrier
	s_setprio 0
	s_add_i32 vcc_lo, vcc_lo, 2
	s_add_u32 s0, s0, 0x100
	s_addc_u32 s1, s1, 0
	s_cmp_gt_u32 vcc_lo, 61
	s_cbranch_scc0 .LBB0_186
	s_and_b64 vcc, exec, s[80:81]
	s_cbranch_vccz .LBB0_189
	s_barrier

; template <class Epi, class Sched, bool ALIGN_EPI = false, bool SP2 = false, bool F8 = false>
; __device__ __forceinline__ void gemm_phase(PG8_LAS unsigned char* lds, const int K, const Sched& S, const Epi& E, const int wave) {
;     ...
; #pragma unroll
;         for (int a = 0; a < 2; ++a)
; #pragma unroll
;             for (int b = 0; b < 2; ++b)
; #pragma unroll
;                 for (int m = 0; m < 4; ++m)
; #pragma unroll
;                     for (int n = 0; n < 2; ++n) acc[a][b][m][n] = (f32x4){0.f, 0.f, 0.f, 0.f};
;         cur = nxt; cA = nA; cB = nB; ++ui;
.LBB0_243:
	s_mov_b32 s40, s82
	s_mov_b32 s41, s84
	s_mov_b64 s[10:11], s[88:89]
	s_mov_b64 s[12:13], s[86:87]
	s_mov_b32 s14, s15

; #define PG8_STAGE(bufoff, gbase, voff) do { _Pragma("unroll") for (int _i = 0; _i < 2; ++_i) \
;         __builtin_amdgcn_global_load_lds((const unsigned*)((const char*)(gbase) + (voff)[_i]), (PG8_LAS unsigned*)(lds + (bufoff) + ldsw + _i * 8192), 16, 0, 0); } while (0)
; #define PG8_LDA(dst, b, h) do { _Pragma("unroll") for (int m = 0; m < 4; ++m) _Pragma("unroll") for (int k = 0; k < 2; ++k) dst[m][k] = *(const PG8_LAS bf16x8*)(lds + PG8_SA(b, h) + aoff + m * 2048 + k * 1024); } while (0)
; #define PG8_LDB(dst, b, h) do { _Pragma("unroll") for (int n = 0; n < 2; ++n) _Pragma("unroll") for (int k = 0; k < 2; ++k) dst[n][k] = *(const PG8_LAS bf16x8*)(lds + PG8_SB(b, h) + boff + n * 2048 + k * 1024); } while (0)
; #define PG8_WAIT_V(n) asm volatile("s_waitcnt vmcnt(" #n ")" ::: "memory")
; #define PG8_WAIT_L(n) asm volatile("s_waitcnt lgkmcnt(" #n ")" ::: "memory")
; #define PG8_BAR __builtin_amdgcn_s_barrier()
; template <class Epi, class Sched, bool ALIGN_EPI = false, bool SP2 = false, bool F8 = false>
; __device__ __forceinline__ void gemm_phase(PG8_LAS unsigned char* lds, const int K, const Sched& S, const Epi& E, const int wave) {
;     ...
;             const bool last = (t == nt - 2);
;             const char* a1 = cA + (size_t)(t + 1) * kstep;
;             const char* a2 = last ? nA : cA + (size_t)(t + 2) * kstep; const char* b2 = last ? nB : cB + (size_t)(t + 2) * kstep;
;             const char* a3 = a2 + kstep; const char* b3 = b2 + kstep;
;             asm volatile("" : "+s"(a1), "+s"(a2), "+s"(b2), "+s"(a3), "+s"(b3));
;             if (last && has_next) S.a_ready(nxt);
;             if constexpr (Epi::KHOOK) { if (cur.prob == 2 ? (t == 16) : (t == 32 || t == 48)) { if (wr == 0) PG8_BAR;
;                 E.khook(acc, cur, (cur.prob == 2 || t == 48) ? 1 : 0, wr, wc, fr, fq); if (wr == 1) PG8_BAR; } }
;             if constexpr (SP2) {
;             PG8_LDB(B0, 0, 0); PG8_LDB(B1, 0, 1); PG8_SCHED; PG8_LDA(At, 0, 0); PG8_STAGE(PG8_SA(1, 1), a1 + hstep, voffA);
;             PG8_WAIT_V(8); PG8_WAIT_L(0); PG8_BAR; PG8_MMA(0, 0, At, B0); PG8_MMA(0, 1, At, B1); PG8_BAR; PG8_SCHED;
;             PG8_LDA(At, 0, 1); PG8_STAGE(PG8_SB(0, 0), b2, voffB); PG8_STAGE(PG8_SB(0, 1), b2 + hstep, voffB); PG8_STAGE(PG8_SA(0, 0), a2, voffA);
;             PG8_WAIT_V(8); PG8_WAIT_L(0); PG8_BAR; PG8_MMA(1, 0, At, B0); PG8_MMA(1, 1, At, B1); PG8_BAR; PG8_SCHED;
.LBB0_247:
	s_mov_b32 s38, -2
	s_mov_b64 s[94:95], 0x100
	s_add_u32 s6, s10, s94
	s_addc_u32 s7, s11, s95
	s_add_u32 s36, s6, 0xffffff80
	s_addc_u32 s37, s7, -1
	s_add_u32 s78, s12, s94
	s_addc_u32 s79, s13, s95
	s_cmp_eq_u32 s38, 28
	s_cselect_b32 s76, s90, s6
	s_cselect_b32 s77, s91, s7
	s_cselect_b32 s7, s93, s79
	s_cselect_b32 s6, s92, s78
	s_add_u32 s96, s76, 0x80
	s_addc_u32 s97, s77, 0
	s_add_u32 s78, s6, 0x80
	s_addc_u32 s79, s7, 0
	v_add_u32_e32 v128, s49, v163
	ds_read_b128 v[140:143], v128
	ds_read_b128 v[144:147], v128 offset:1024
	ds_read_b128 v[148:151], v128 offset:2048
	ds_read_b128 v[152:155], v128 offset:3072
	v_add_u32_e32 v128, s50, v163
	ds_read_b128 v[168:171], v128
	ds_read_b128 v[172:175], v128 offset:1024
	ds_read_b128 v[176:179], v128 offset:2048
	ds_read_b128 v[180:183], v128 offset:3072
	s_add_u32 s36, s36, 0x100000
	s_addc_u32 s37, s37, 0
	v_lshl_add_u64 v[128:129], s[36:37], 0, v[134:135]
	s_add_i32 m0, s42, 0xc000
	ds_read_b128 v[184:187], v165
	ds_read_b128 v[188:191], v165 offset:1024
	ds_read_b128 v[192:195], v165 offset:2048
	ds_read_b128 v[196:199], v165 offset:3072
	ds_read_b128 v[200:203], v165 offset:4096
	ds_read_b128 v[204:207], v165 offset:5120
	ds_read_b128 v[208:211], v165 offset:6144
	ds_read_b128 v[212:215], v165 offset:7168
	global_load_lds_dwordx4 v[128:129], off
	v_lshl_add_u64 v[128:129], s[36:37], 0, v[160:161]
	s_add_i32 m0, s42, 0xe000
	s_nop 0
	global_load_lds_dwordx4 v[128:129], off
	s_waitcnt vmcnt(8)
	s_waitcnt lgkmcnt(0)
	s_setprio 1
	s_barrier
	v_mfma_scale_f32_16x16x128_f8f6f4 v[124:127], v[140:147], v[184:191], 0, v166, v166 op_sel_hi:[0, 0, 0]
	v_mfma_scale_f32_16x16x128_f8f6f4 v[120:123], v[148:155], v[184:191], 0, v166, v166 op_sel_hi:[0, 0, 0]
	v_mfma_scale_f32_16x16x128_f8f6f4 v[116:119], v[140:147], v[192:199], 0, v166, v166 op_sel_hi:[0, 0, 0]
	v_mfma_scale_f32_16x16x128_f8f6f4 v[112:115], v[148:155], v[192:199], 0, v166, v166 op_sel_hi:[0, 0, 0]
	v_mfma_scale_f32_16x16x128_f8f6f4 v[108:111], v[140:147], v[200:207], 0, v166, v166 op_sel_hi:[0, 0, 0]
	v_mfma_scale_f32_16x16x128_f8f6f4 v[104:107], v[148:155], v[200:207], 0, v166, v166 op_sel_hi:[0, 0, 0]
	v_mfma_scale_f32_16x16x128_f8f6f4 v[100:103], v[140:147], v[208:215], 0, v166, v166 op_sel_hi:[0, 0, 0]
	v_mfma_scale_f32_16x16x128_f8f6f4 v[96:99], v[148:155], v[208:215], 0, v166, v166 op_sel_hi:[0, 0, 0]
	v_mfma_scale_f32_16x16x128_f8f6f4 v[156:159], v[168:175], v[184:191], 0, v166, v166 op_sel_hi:[0, 0, 0]
	v_mfma_scale_f32_16x16x128_f8f6f4 v[184:187], v[176:183], v[184:191], 0, v166, v166 op_sel_hi:[0, 0, 0]
	v_mfma_scale_f32_16x16x128_f8f6f4 v[188:191], v[168:175], v[192:199], 0, v166, v166 op_sel_hi:[0, 0, 0]
	v_mfma_scale_f32_16x16x128_f8f6f4 v[192:195], v[176:183], v[192:199], 0, v166, v166 op_sel_hi:[0, 0, 0]
	v_mfma_scale_f32_16x16x128_f8f6f4 v[196:199], v[168:175], v[200:207], 0, v166, v166 op_sel_hi:[0, 0, 0]
	v_mfma_scale_f32_16x16x128_f8f6f4 v[200:203], v[176:183], v[200:207], 0, v166, v166 op_sel_hi:[0, 0, 0]
	v_mfma_scale_f32_16x16x128_f8f6f4 v[204:207], v[168:175], v[208:215], 0, v166, v166 op_sel_hi:[0, 0, 0]
	v_mfma_scale_f32_16x16x128_f8f6f4 v[208:211], v[176:183], v[208:215], 0, v166, v166 op_sel_hi:[0, 0, 0]
	s_barrier
	s_setprio 0
	s_add_i32 s36, s49, s74
	v_lshl_add_u64 v[128:129], s[6:7], 0, v[132:133]
	s_mov_b32 m0, s36
	s_nop 1
	ds_read_b128 v[64:67], v165 offset:16384
	ds_read_b128 v[68:71], v165 offset:17408
	ds_read_b128 v[72:75], v165 offset:18432
	ds_read_b128 v[76:79], v165 offset:19456
	ds_read_b128 v[80:83], v165 offset:20480
	ds_read_b128 v[84:87], v165 offset:21504
	ds_read_b128 v[88:91], v165 offset:22528
	ds_read_b128 v[92:95], v165 offset:23552
	global_load_lds_dwordx4 v[128:129], off
	s_add_i32 m0, s36, 0x2000
	v_lshl_add_u64 v[128:129], s[6:7], 0, v[252:253]
	s_add_u32 s6, s6, 0x100000
	s_addc_u32 s7, s7, 0
	s_add_i32 s36, s50, s74
	global_load_lds_dwordx4 v[128:129], off
	v_lshl_add_u64 v[128:129], s[6:7], 0, v[132:133]
	s_mov_b32 m0, s36
	s_nop 0
	global_load_lds_dwordx4 v[128:129], off
	v_lshl_add_u64 v[128:129], s[6:7], 0, v[252:253]
	s_add_i32 m0, s36, 0x2000
	s_nop 0
	global_load_lds_dwordx4 v[128:129], off
	v_lshl_add_u64 v[128:129], s[76:77], 0, v[134:135]
	s_mov_b32 m0, s42
	s_nop 0
	global_load_lds_dwordx4 v[128:129], off
	v_lshl_add_u64 v[128:129], s[76:77], 0, v[160:161]
	s_mov_b32 m0, s43
	s_nop 0
	global_load_lds_dwordx4 v[128:129], off
	s_waitcnt vmcnt(8)
	s_waitcnt lgkmcnt(0)
	s_setprio 1
	s_barrier
	v_mfma_scale_f32_16x16x128_f8f6f4 v[60:63], v[140:147], v[64:71], 0, v166, v166 op_sel_hi:[0, 0, 0]
	v_mfma_scale_f32_16x16x128_f8f6f4 v[56:59], v[148:155], v[64:71], 0, v166, v166 op_sel_hi:[0, 0, 0]
	v_mfma_scale_f32_16x16x128_f8f6f4 v[52:55], v[140:147], v[72:79], 0, v166, v166 op_sel_hi:[0, 0, 0]
	v_mfma_scale_f32_16x16x128_f8f6f4 v[48:51], v[148:155], v[72:79], 0, v166, v166 op_sel_hi:[0, 0, 0]
	v_mfma_scale_f32_16x16x128_f8f6f4 v[212:215], v[140:147], v[80:87], 0, v166, v166 op_sel_hi:[0, 0, 0]
	v_mfma_scale_f32_16x16x128_f8f6f4 v[216:219], v[148:155], v[80:87], 0, v166, v166 op_sel_hi:[0, 0, 0]
	v_mfma_scale_f32_16x16x128_f8f6f4 v[220:223], v[140:147], v[88:95], 0, v166, v166 op_sel_hi:[0, 0, 0]
	v_mfma_scale_f32_16x16x128_f8f6f4 v[224:227], v[148:155], v[88:95], 0, v166, v166 op_sel_hi:[0, 0, 0]
	v_mfma_scale_f32_16x16x128_f8f6f4 v[228:231], v[168:175], v[64:71], 0, v166, v166 op_sel_hi:[0, 0, 0]
	v_mfma_scale_f32_16x16x128_f8f6f4 v[236:239], v[176:183], v[64:71], 0, v166, v166 op_sel_hi:[0, 0, 0]
	v_mfma_scale_f32_16x16x128_f8f6f4 v[244:247], v[168:175], v[72:79], 0, v166, v166 op_sel_hi:[0, 0, 0]
	v_mfma_scale_f32_16x16x128_f8f6f4 v[248:251], v[176:183], v[72:79], 0, v166, v166 op_sel_hi:[0, 0, 0]
	v_mfma_scale_f32_16x16x128_f8f6f4 v[232:235], v[168:175], v[80:87], 0, v166, v166 op_sel_hi:[0, 0, 0]
	v_mfma_scale_f32_16x16x128_f8f6f4 v[240:243], v[176:183], v[80:87], 0, v166, v166 op_sel_hi:[0, 0, 0]
	v_mfma_scale_f32_16x16x128_f8f6f4 v[136:139], v[168:175], v[88:95], 0, v166, v166 op_sel_hi:[0, 0, 0]
	v_mfma_scale_f32_16x16x128_f8f6f4 v[128:131], v[176:183], v[88:95], 0, v166, v166 op_sel_hi:[0, 0, 0]
	s_barrier
	s_branch .Lmid_k248

; #define PG8_STAGE(bufoff, gbase, voff) do { _Pragma("unroll") for (int _i = 0; _i < 2; ++_i) \
;         __builtin_amdgcn_global_load_lds((const unsigned*)((const char*)(gbase) + (voff)[_i]), (PG8_LAS unsigned*)(lds + (bufoff) + ldsw + _i * 8192), 16, 0, 0); } while (0)
; #define PG8_LDA(dst, b, h) do { _Pragma("unroll") for (int m = 0; m < 4; ++m) _Pragma("unroll") for (int k = 0; k < 2; ++k) dst[m][k] = *(const PG8_LAS bf16x8*)(lds + PG8_SA(b, h) + aoff + m * 2048 + k * 1024); } while (0)
; #define PG8_LDB(dst, b, h) do { _Pragma("unroll") for (int n = 0; n < 2; ++n) _Pragma("unroll") for (int k = 0; k < 2; ++k) dst[n][k] = *(const PG8_LAS bf16x8*)(lds + PG8_SB(b, h) + boff + n * 2048 + k * 1024); } while (0)
; #define PG8_WAIT_V(n) asm volatile("s_waitcnt vmcnt(" #n ")" ::: "memory")
; #define PG8_WAIT_L(n) asm volatile("s_waitcnt lgkmcnt(" #n ")" ::: "memory")
; #define PG8_BAR __builtin_amdgcn_s_barrier()
; #define PG8_SCHED __builtin_amdgcn_sched_barrier(0)
; template <class Epi, class Sched, bool ALIGN_EPI = false, bool SP2 = false, bool F8 = false>
; __device__ __forceinline__ void gemm_phase(PG8_LAS unsigned char* lds, const int K, const Sched& S, const Epi& E, const int wave) {
;     ...
;             PG8_LDB(B0, 1, 0); PG8_LDB(B1, 1, 1); PG8_SCHED; PG8_LDA(At, 1, 0); PG8_STAGE(PG8_SA(0, 1), a2 + hstep, voffA);
;             PG8_WAIT_V(8); PG8_WAIT_L(0); PG8_BAR; PG8_MMA(0, 0, At, B0); PG8_MMA(0, 1, At, B1); PG8_BAR; PG8_SCHED;
;             PG8_LDA(At, 1, 1); PG8_STAGE(PG8_SB(1, 0), b3, voffB); PG8_STAGE(PG8_SB(1, 1), b3 + hstep, voffB); PG8_STAGE(PG8_SA(1, 0), a3, voffA);
;             PG8_WAIT_V(8); PG8_WAIT_L(0); PG8_BAR; PG8_MMA(1, 0, At, B0); PG8_MMA(1, 1, At, B1); PG8_BAR; PG8_SCHED;
.Lmid_k248:
	s_setprio 0
	s_add_i32 s36, 0, 0x18000
	s_add_i32 s37, 0, 0x1c000
	v_add_u32_e32 v12, s36, v163
	v_add_u32_e32 v16, s37, v163
	s_nop 0
	ds_read_b128 v[0:3], v12
	ds_read_b128 v[4:7], v12 offset:1024
	ds_read_b128 v[8:11], v12 offset:2048
	ds_read_b128 v[12:15], v12 offset:3072
	ds_read_b128 v[140:143], v16
	ds_read_b128 v[144:147], v16 offset:1024
	ds_read_b128 v[148:151], v16 offset:2048
	ds_read_b128 v[152:155], v16 offset:3072
	s_add_u32 s6, s76, 0x100000
	s_addc_u32 s7, s77, 0
	s_mov_b32 m0, s44
	v_lshl_add_u64 v[64:65], s[6:7], 0, v[134:135]
	ds_read_b128 v[16:19], v165 offset:32768
	ds_read_b128 v[20:23], v165 offset:33792
	ds_read_b128 v[24:27], v165 offset:34816
	ds_read_b128 v[28:31], v165 offset:35840
	ds_read_b128 v[32:35], v165 offset:36864
	ds_read_b128 v[36:39], v165 offset:37888
	ds_read_b128 v[40:43], v165 offset:38912
	ds_read_b128 v[44:47], v165 offset:39936
	global_load_lds_dwordx4 v[64:65], off
	v_lshl_add_u64 v[64:65], s[6:7], 0, v[160:161]
	s_mov_b32 m0, s45
	s_nop 0
	global_load_lds_dwordx4 v[64:65], off
	s_waitcnt vmcnt(8)
	s_waitcnt lgkmcnt(0)
	s_setprio 1
	s_barrier
	v_mfma_scale_f32_16x16x128_f8f6f4 v[124:127], v[0:7], v[16:23], v[124:127], v166, v166 op_sel_hi:[0,0,0]
	v_mfma_scale_f32_16x16x128_f8f6f4 v[120:123], v[8:15], v[16:23], v[120:123], v166, v166 op_sel_hi:[0,0,0]
	v_mfma_scale_f32_16x16x128_f8f6f4 v[116:119], v[0:7], v[24:31], v[116:119], v166, v166 op_sel_hi:[0,0,0]
	v_mfma_scale_f32_16x16x128_f8f6f4 v[112:115], v[8:15], v[24:31], v[112:115], v166, v166 op_sel_hi:[0,0,0]
	v_mfma_scale_f32_16x16x128_f8f6f4 v[108:111], v[0:7], v[32:39], v[108:111], v166, v166 op_sel_hi:[0,0,0]
	v_mfma_scale_f32_16x16x128_f8f6f4 v[104:107], v[8:15], v[32:39], v[104:107], v166, v166 op_sel_hi:[0,0,0]
	v_mfma_scale_f32_16x16x128_f8f6f4 v[100:103], v[0:7], v[40:47], v[100:103], v166, v166 op_sel_hi:[0,0,0]
	v_mfma_scale_f32_16x16x128_f8f6f4 v[96:99], v[8:15], v[40:47], v[96:99], v166, v166 op_sel_hi:[0,0,0]
	v_mfma_scale_f32_16x16x128_f8f6f4 v[92:95], v[140:147], v[16:23], v[156:159], v166, v166 op_sel_hi:[0,0,0]
	v_mfma_scale_f32_16x16x128_f8f6f4 v[88:91], v[148:155], v[16:23], v[184:187], v166, v166 op_sel_hi:[0,0,0]
	v_mfma_scale_f32_16x16x128_f8f6f4 v[84:87], v[140:147], v[24:31], v[188:191], v166, v166 op_sel_hi:[0,0,0]
	v_mfma_scale_f32_16x16x128_f8f6f4 v[80:83], v[148:155], v[24:31], v[192:195], v166, v166 op_sel_hi:[0,0,0]
	v_mfma_scale_f32_16x16x128_f8f6f4 v[76:79], v[140:147], v[32:39], v[196:199], v166, v166 op_sel_hi:[0,0,0]
	v_mfma_scale_f32_16x16x128_f8f6f4 v[72:75], v[148:155], v[32:39], v[200:203], v166, v166 op_sel_hi:[0,0,0]
	v_mfma_scale_f32_16x16x128_f8f6f4 v[68:71], v[140:147], v[40:47], v[204:207], v166, v166 op_sel_hi:[0,0,0]
	v_mfma_scale_f32_16x16x128_f8f6f4 v[64:67], v[148:155], v[40:47], v[208:211], v166, v166 op_sel_hi:[0,0,0]
	s_barrier
	s_setprio 0
	s_add_i32 s6, s36, s74
	v_lshl_add_u64 v[24:25], s[78:79], 0, v[132:133]
	s_mov_b32 m0, s6
	ds_read_b128 v[16:19], v165 offset:49152
	ds_read_b128 v[20:23], v165 offset:50176
	ds_read_b128 v[168:171], v165 offset:51200
	ds_read_b128 v[172:175], v165 offset:52224
	ds_read_b128 v[176:179], v165 offset:53248
	ds_read_b128 v[180:183], v165 offset:54272
	ds_read_b128 v[184:187], v165 offset:55296
	ds_read_b128 v[188:191], v165 offset:56320
	global_load_lds_dwordx4 v[24:25], off
	s_add_i32 m0, s6, 0x2000
	s_add_u32 s6, s78, 0x100000
	v_lshl_add_u64 v[24:25], s[78:79], 0, v[252:253]
	s_addc_u32 s7, s79, 0
	s_add_i32 s36, s37, s74
	global_load_lds_dwordx4 v[24:25], off
	v_lshl_add_u64 v[24:25], s[6:7], 0, v[132:133]
	s_mov_b32 m0, s36
	s_nop 0
	global_load_lds_dwordx4 v[24:25], off
	v_lshl_add_u64 v[24:25], s[6:7], 0, v[252:253]
	s_add_i32 m0, s36, 0x2000
	s_nop 0
	global_load_lds_dwordx4 v[24:25], off
	v_lshl_add_u64 v[24:25], s[96:97], 0, v[134:135]
	s_mov_b32 m0, s46
	s_nop 0
	global_load_lds_dwordx4 v[24:25], off
	v_lshl_add_u64 v[24:25], s[96:97], 0, v[160:161]
	s_mov_b32 m0, s47
	s_nop 0
	global_load_lds_dwordx4 v[24:25], off
	s_waitcnt vmcnt(8)
	s_waitcnt lgkmcnt(0)
	s_setprio 1
	s_barrier
	v_mfma_scale_f32_16x16x128_f8f6f4 v[60:63], v[0:7], v[16:23], v[60:63], v166, v166 op_sel_hi:[0,0,0]
	v_mfma_scale_f32_16x16x128_f8f6f4 v[56:59], v[8:15], v[16:23], v[56:59], v166, v166 op_sel_hi:[0,0,0]
	v_mfma_scale_f32_16x16x128_f8f6f4 v[52:55], v[0:7], v[168:175], v[52:55], v166, v166 op_sel_hi:[0,0,0]
	v_mfma_scale_f32_16x16x128_f8f6f4 v[48:51], v[8:15], v[168:175], v[48:51], v166, v166 op_sel_hi:[0,0,0]
	v_mfma_scale_f32_16x16x128_f8f6f4 v[44:47], v[0:7], v[176:183], v[212:215], v166, v166 op_sel_hi:[0,0,0]
	v_mfma_scale_f32_16x16x128_f8f6f4 v[40:43], v[8:15], v[176:183], v[216:219], v166, v166 op_sel_hi:[0,0,0]
	v_mfma_scale_f32_16x16x128_f8f6f4 v[36:39], v[0:7], v[184:191], v[220:223], v166, v166 op_sel_hi:[0,0,0]
	v_mfma_scale_f32_16x16x128_f8f6f4 v[32:35], v[8:15], v[184:191], v[224:227], v166, v166 op_sel_hi:[0,0,0]
	v_mfma_scale_f32_16x16x128_f8f6f4 v[28:31], v[140:147], v[16:23], v[228:231], v166, v166 op_sel_hi:[0,0,0]
	v_mfma_scale_f32_16x16x128_f8f6f4 v[24:27], v[148:155], v[16:23], v[236:239], v166, v166 op_sel_hi:[0,0,0]
	v_mfma_scale_f32_16x16x128_f8f6f4 v[20:23], v[140:147], v[168:175], v[244:247], v166, v166 op_sel_hi:[0,0,0]
	v_mfma_scale_f32_16x16x128_f8f6f4 v[16:19], v[148:155], v[168:175], v[248:251], v166, v166 op_sel_hi:[0,0,0]
	v_mfma_scale_f32_16x16x128_f8f6f4 v[12:15], v[140:147], v[176:183], v[232:235], v166, v166 op_sel_hi:[0,0,0]
	v_mfma_scale_f32_16x16x128_f8f6f4 v[8:11], v[148:155], v[176:183], v[240:243], v166, v166 op_sel_hi:[0,0,0]
	v_mfma_scale_f32_16x16x128_f8f6f4 v[4:7], v[140:147], v[184:191], v[136:139], v166, v166 op_sel_hi:[0,0,0]
	v_mfma_scale_f32_16x16x128_f8f6f4 v[0:3], v[148:155], v[184:191], v[128:131], v166, v166 op_sel_hi:[0,0,0]
	s_barrier
	s_setprio 0
	s_add_i32 s38, s38, 2
	s_add_u32 s94, s94, 0x100
	s_addc_u32 s95, s95, 0
	s_cmp_gt_u32 s38, 29
	s_cbranch_scc0 .LBB0_248
	s_and_b64 vcc, exec, s[60:61]
	s_cbranch_vccz .LBB0_251
	s_barrier

; #define PG8_STAGE(bufoff, gbase, voff) do { _Pragma("unroll") for (int _i = 0; _i < 2; ++_i) \
;         __builtin_amdgcn_global_load_lds((const unsigned*)((const char*)(gbase) + (voff)[_i]), (PG8_LAS unsigned*)(lds + (bufoff) + ldsw + _i * 8192), 16, 0, 0); } while (0)
; #define PG8_WAIT_V(n) asm volatile("s_waitcnt vmcnt(" #n ")" ::: "memory")
; #define PG8_BAR __builtin_amdgcn_s_barrier()
; template <class Epi, class Sched, bool ALIGN_EPI = false, bool SP2 = false, bool F8 = false>
; __device__ __forceinline__ void gemm_phase(PG8_LAS unsigned char* lds, const int K, const Sched& S, const Epi& E, const int wave) {
;     ...
;     f32x4 acc[2][2][4][2];
; #pragma unroll
;     for (int a = 0; a < 2; ++a)
; #pragma unroll
;         for (int b = 0; b < 2; ++b)
; #pragma unroll
;             for (int m = 0; m < 4; ++m)
; #pragma unroll
;                 for (int n = 0; n < 2; ++n) acc[a][b][m][n] = (f32x4){0.f, 0.f, 0.f, 0.f};
;     ...
;         PG8_STAGE(PG8_SB(0, 0), cB, voffB); PG8_STAGE(PG8_SB(0, 1), cB + hstep, voffB); PG8_STAGE(PG8_SA(0, 0), cA, voffA); PG8_STAGE(PG8_SA(0, 1), cA + hstep, voffA);
;         if (wr == 1) PG8_BAR;
;         PG8_WAIT_V(2); PG8_BAR;
;         PG8_STAGE(PG8_SB(1, 0), cB + kstep, voffB); PG8_STAGE(PG8_SA(1, 0), cA + kstep, voffA); PG8_STAGE(PG8_SB(1, 1), cB + hstep + kstep, voffB);
;         PG8_WAIT_V(6); PG8_BAR;
.LBB0_936:
	s_add_u32 s18, s34, 0x3d400000
	s_addc_u32 s19, s35, 0
	s_add_u32 s72, s34, 0x10000
	s_mov_b64 s[0:1], 0x80
	s_addc_u32 s73, s35, 0
	s_add_i32 m0, s64, 0x18000
	v_lshl_add_u64 v[8:9], v[8:9], 0, s[0:1]
	s_bfe_u32 s7, s94, 0x20006
	s_waitcnt vmcnt(2)
	s_barrier
	global_load_lds_dwordx4 v[8:9], off
	v_lshl_add_u64 v[6:7], v[6:7], 0, s[0:1]
	s_add_i32 m0, s64, 0x1a000
	s_add_i32 s74, s64, 0x8000
	s_lshl_b32 s8, s6, 13
	s_lshl_b32 s9, s7, 12
	global_load_lds_dwordx4 v[6:7], off
	v_lshl_add_u64 v[2:3], v[2:3], 0, s[0:1]
	s_mov_b32 m0, s74
	s_add_i32 s76, s64, 0xa000
	global_load_lds_dwordx4 v[2:3], off
	v_lshl_add_u64 v[2:3], v[4:5], 0, s[0:1]
	s_add_u32 s0, s14, 0x100080
	s_mov_b32 m0, s76
	s_addc_u32 s1, s15, 0
	global_load_lds_dwordx4 v[2:3], off
	s_add_i32 m0, s64, 0x1c000
	v_lshl_add_u64 v[2:3], s[0:1], 0, v[142:143]
	global_load_lds_dwordx4 v[2:3], off
	v_lshl_add_u64 v[2:3], s[0:1], 0, v[146:147]
	s_add_i32 m0, s64, 0x1e000
	s_cmpk_lt_u32 s94, 0x100
	global_load_lds_dwordx4 v[2:3], off
	v_lshrrev_b32_e32 v3, 1, v10
	v_and_b32_e32 v3, 24, v3
	v_and_b32_e32 v2, 15, v10
	v_lshlrev_b32_e32 v4, 1, v3
	v_lshl_or_b32 v167, s6, 6, v2
	v_lshl_or_b32 v2, v2, 6, v4
	v_lshlrev_b32_e32 v4, 2, v10
	v_and_b32_e32 v4, 32, v4
	v_bitop3_b32 v5, v2, s8, v4 bitop3:0xde
	v_bitop3_b32 v168, v2, s9, v4 bitop3:0xde
	s_waitcnt vmcnt(6)
	s_cselect_b64 s[20:21], -1, 0
	s_or_b32 s6, s7, s6
	v_lshl_or_b32 v169, s7, 5, v3
	v_mov_b32_e32 v2, v0
	v_mov_b32_e32 v3, v0
	v_cndmask_b32_e64 v4, 0, 1, s[4:5]
	v_cmp_eq_u32_e64 s[0:1], 0, v1
	s_cmp_eq_u32 s6, 0
	v_mov_b32_e32 v1, v0
	v_cmp_ne_u32_e64 s[4:5], 1, v4
	v_add_u32_e32 v170, 0, v5
	s_cselect_b64 s[22:23], -1, 0
	s_add_i32 s77, 0, 0x10000
	s_add_i32 s78, 0, 0x14000
	s_movk_i32 s79, 0x3fff
	v_mov_b64_e32 v[148:149], 0x3ff
	v_mov_b64_e32 v[150:151], 0x7f
	v_mov_b64_e32 v[152:153], 0x80
	v_mov_b64_e32 v[154:155], 0x3d0901
	s_barrier
	s_branch .LBB0_939
.LBB0_937:
	v_mov_b32_e32 v2, v0
	v_mov_b32_e32 v3, v0
	v_mov_b32_e32 v1, v0
	s_mov_b32 s62, s82
	s_mov_b32 s3, s81
	s_mov_b32 s60, s24
	s_mov_b32 s61, s30
	s_mov_b64 s[12:13], s[26:27]
	s_mov_b64 s[14:15], s[28:29]
	s_mov_b32 s75, s80

; #define PG8_STAGE(bufoff, gbase, voff) do { _Pragma("unroll") for (int _i = 0; _i < 2; ++_i) \
;         __builtin_amdgcn_global_load_lds((const unsigned*)((const char*)(gbase) + (voff)[_i]), (PG8_LAS unsigned*)(lds + (bufoff) + ldsw + _i * 8192), 16, 0, 0); } while (0)
; #define PG8_LDA(dst, b, h) do { _Pragma("unroll") for (int m = 0; m < 4; ++m) _Pragma("unroll") for (int k = 0; k < 2; ++k) dst[m][k] = *(const PG8_LAS bf16x8*)(lds + PG8_SA(b, h) + aoff + m * 2048 + k * 1024); } while (0)
; #define PG8_LDB(dst, b, h) do { _Pragma("unroll") for (int n = 0; n < 2; ++n) _Pragma("unroll") for (int k = 0; k < 2; ++k) dst[n][k] = *(const PG8_LAS bf16x8*)(lds + PG8_SB(b, h) + boff + n * 2048 + k * 1024); } while (0)
; #define PG8_WAIT_V(n) asm volatile("s_waitcnt vmcnt(" #n ")" ::: "memory")
; #define PG8_WAIT_L(n) asm volatile("s_waitcnt lgkmcnt(" #n ")" ::: "memory")
; #define PG8_BAR __builtin_amdgcn_s_barrier()
; #define PG8_SCHED __builtin_amdgcn_sched_barrier(0)
; template <class Epi, class Sched, bool ALIGN_EPI = false, bool SP2 = false, bool F8 = false>
; __device__ __forceinline__ void gemm_phase(PG8_LAS unsigned char* lds, const int K, const Sched& S, const Epi& E, const int wave) {
;     ...
;         const bool has_next = S.next(ui + 1, nxt);
;         const char* nA = has_next ? nxt.a : cA; const char* nB = has_next ? nxt.b : cB;
;         const int nt = cur.nt;
;         for (int t = 0; t < nt; t += 2) {
;             const bool last = (t == nt - 2);
;             const char* a1 = cA + (size_t)(t + 1) * kstep;
;             const char* a2 = last ? nA : cA + (size_t)(t + 2) * kstep; const char* b2 = last ? nB : cB + (size_t)(t + 2) * kstep;
;             const char* a3 = a2 + kstep; const char* b3 = b2 + kstep;
;             asm volatile("" : "+s"(a1), "+s"(a2), "+s"(b2), "+s"(a3), "+s"(b3));
;             if (last && has_next) S.a_ready(nxt);
;             if constexpr (Epi::KHOOK) { if (cur.prob == 2 ? (t == 16) : (t == 32 || t == 48)) { if (wr == 0) PG8_BAR;
;                 E.khook(acc, cur, (cur.prob == 2 || t == 48) ? 1 : 0, wr, wc, fr, fq); if (wr == 1) PG8_BAR; } }
;             if constexpr (SP2) {
;             PG8_LDB(B0, 0, 0); PG8_LDB(B1, 0, 1); PG8_SCHED; PG8_LDA(At, 0, 0); PG8_STAGE(PG8_SA(1, 1), a1 + hstep, voffA);
;             PG8_WAIT_V(8); PG8_WAIT_L(0); PG8_BAR; PG8_MMA(0, 0, At, B0); PG8_MMA(0, 1, At, B1); PG8_BAR; PG8_SCHED;
.LBB0_964:
	s_xor_b64 s[36:37], s[38:39], -1
	s_cmp_lt_i32 s62, 1
	s_cbranch_scc1 .LBB0_967
	s_and_b64 s[6:7], s[38:39], exec
	s_cselect_b32 s25, s27, s13
	s_cselect_b32 s31, s26, s12
	s_cselect_b32 s83, s29, s15
	s_cselect_b32 s84, s28, s14
	s_add_i32 s85, s62, -2
	s_add_u32 s86, s12, 0x100
	s_addc_u32 s87, s13, 0
	s_add_u32 s88, s14, 0x100
	s_addc_u32 s89, s15, 0
	s_add_u32 s6, s12, 0x80
	s_addc_u32 s7, s13, 0
	s_mov_b32 s8, 0
	s_add_i32 s90, s8, 2
	s_cmp_eq_u32 s85, s8
	s_cselect_b32 s42, s31, s86
	s_cselect_b32 s43, s25, s87
	s_cselect_b32 s57, s83, s89
	s_cselect_b32 s56, s84, s88
	s_add_u32 s8, s42, 0x80
	s_addc_u32 s9, s43, 0
	s_add_u32 s40, s56, 0x80
	s_addc_u32 s41, s57, 0
	s_mov_b64 s[92:93], s[6:7]
	v_add_u32_e32 v1, s77, v168
	ds_read_b128 v[132:135], v1
	ds_read_b128 v[136:139], v1 offset:1024
	ds_read_b128 v[156:159], v1 offset:2048
	ds_read_b128 v[160:163], v1 offset:3072
	v_add_u32_e32 v1, s78, v168
	ds_read_b128 v[172:175], v1
	ds_read_b128 v[176:179], v1 offset:1024
	ds_read_b128 v[180:183], v1 offset:2048
	ds_read_b128 v[184:187], v1 offset:3072
	s_add_u32 s92, s92, 0x100000
	s_addc_u32 s93, s93, 0
	v_lshl_add_u64 v[2:3], s[92:93], 0, v[140:141]
	s_add_i32 m0, s64, 0xc000
	ds_read_b128 v[188:191], v170
	ds_read_b128 v[192:195], v170 offset:1024
	ds_read_b128 v[196:199], v170 offset:2048
	ds_read_b128 v[200:203], v170 offset:3072
	ds_read_b128 v[204:207], v170 offset:4096
	ds_read_b128 v[208:211], v170 offset:5120
	ds_read_b128 v[212:215], v170 offset:6144
	ds_read_b128 v[216:219], v170 offset:7168
	global_load_lds_dwordx4 v[2:3], off
	v_lshl_add_u64 v[2:3], s[92:93], 0, v[144:145]
	s_add_i32 m0, s64, 0xe000
	s_nop 0
	global_load_lds_dwordx4 v[2:3], off
	s_waitcnt vmcnt(8)
	s_waitcnt lgkmcnt(0)
	s_setprio 1
	s_barrier
	v_mfma_f32_16x16x32_bf16 v[128:131], v[132:135], v[188:191], 0
	v_mfma_f32_16x16x32_bf16 v[124:127], v[156:159], v[188:191], 0
	v_mfma_f32_16x16x32_bf16 v[120:123], v[132:135], v[196:199], 0
	v_mfma_f32_16x16x32_bf16 v[116:119], v[156:159], v[196:199], 0
	v_mfma_f32_16x16x32_bf16 v[112:115], v[132:135], v[204:207], 0
	v_mfma_f32_16x16x32_bf16 v[108:111], v[156:159], v[204:207], 0
	v_mfma_f32_16x16x32_bf16 v[104:107], v[132:135], v[212:215], 0
	v_mfma_f32_16x16x32_bf16 v[100:103], v[156:159], v[212:215], 0
	v_mfma_f32_16x16x32_bf16 v[128:131], v[136:139], v[192:195], v[128:131]
	v_mfma_f32_16x16x32_bf16 v[124:127], v[160:163], v[192:195], v[124:127]
	v_mfma_f32_16x16x32_bf16 v[120:123], v[136:139], v[200:203], v[120:123]
	v_mfma_f32_16x16x32_bf16 v[116:119], v[160:163], v[200:203], v[116:119]
	v_mfma_f32_16x16x32_bf16 v[112:115], v[136:139], v[208:211], v[112:115]
	v_mfma_f32_16x16x32_bf16 v[108:111], v[160:163], v[208:211], v[108:111]
	v_mfma_f32_16x16x32_bf16 v[104:107], v[136:139], v[216:219], v[104:107]
	v_mfma_f32_16x16x32_bf16 v[100:103], v[160:163], v[216:219], v[100:103]
	v_mfma_f32_16x16x32_bf16 v[96:99], v[172:175], v[188:191], 0
	v_mfma_f32_16x16x32_bf16 v[92:95], v[180:183], v[188:191], 0
	v_mfma_f32_16x16x32_bf16 v[88:91], v[172:175], v[196:199], 0
	v_mfma_f32_16x16x32_bf16 v[84:87], v[180:183], v[196:199], 0
	v_mfma_f32_16x16x32_bf16 v[80:83], v[172:175], v[204:207], 0
	v_mfma_f32_16x16x32_bf16 v[76:79], v[180:183], v[204:207], 0
	v_mfma_f32_16x16x32_bf16 v[72:75], v[172:175], v[212:215], 0
	v_mfma_f32_16x16x32_bf16 v[68:71], v[180:183], v[212:215], 0
	v_mfma_f32_16x16x32_bf16 v[96:99], v[176:179], v[192:195], v[96:99]
	v_mfma_f32_16x16x32_bf16 v[92:95], v[184:187], v[192:195], v[92:95]
	v_mfma_f32_16x16x32_bf16 v[88:91], v[176:179], v[200:203], v[88:91]
	v_mfma_f32_16x16x32_bf16 v[84:87], v[184:187], v[200:203], v[84:87]
	v_mfma_f32_16x16x32_bf16 v[80:83], v[176:179], v[208:211], v[80:83]
	v_mfma_f32_16x16x32_bf16 v[76:79], v[184:187], v[208:211], v[76:79]
	v_mfma_f32_16x16x32_bf16 v[72:75], v[176:179], v[216:219], v[72:75]
	v_mfma_f32_16x16x32_bf16 v[68:71], v[184:187], v[216:219], v[68:71]
	s_barrier
; #define PG8_STAGE(bufoff, gbase, voff) do { _Pragma("unroll") for (int _i = 0; _i < 2; ++_i) \
;         __builtin_amdgcn_global_load_lds((const unsigned*)((const char*)(gbase) + (voff)[_i]), (PG8_LAS unsigned*)(lds + (bufoff) + ldsw + _i * 8192), 16, 0, 0); } while (0)
; #define PG8_LDA(dst, b, h) do { _Pragma("unroll") for (int m = 0; m < 4; ++m) _Pragma("unroll") for (int k = 0; k < 2; ++k) dst[m][k] = *(const PG8_LAS bf16x8*)(lds + PG8_SA(b, h) + aoff + m * 2048 + k * 1024); } while (0)
; #define PG8_WAIT_V(n) asm volatile("s_waitcnt vmcnt(" #n ")" ::: "memory")
; #define PG8_WAIT_L(n) asm volatile("s_waitcnt lgkmcnt(" #n ")" ::: "memory")
; #define PG8_BAR __builtin_amdgcn_s_barrier()
; #define PG8_SCHED __builtin_amdgcn_sched_barrier(0)
; template <class Epi, class Sched, bool ALIGN_EPI = false, bool SP2 = false, bool F8 = false>
; __device__ __forceinline__ void gemm_phase(PG8_LAS unsigned char* lds, const int K, const Sched& S, const Epi& E, const int wave) {
;     ...
;             PG8_LDA(At, 0, 1); PG8_STAGE(PG8_SB(0, 0), b2, voffB); PG8_STAGE(PG8_SB(0, 1), b2 + hstep, voffB); PG8_STAGE(PG8_SA(0, 0), a2, voffA);
;             PG8_WAIT_V(8); PG8_WAIT_L(0); PG8_BAR; PG8_MMA(1, 0, At, B0); PG8_MMA(1, 1, At, B1); PG8_BAR; PG8_SCHED;
	s_setprio 0
	s_add_i32 s91, s77, s63
	v_lshl_add_u64 v[2:3], s[56:57], 0, v[142:143]
	s_mov_b32 m0, s91
	ds_read_b128 v[188:191], v170 offset:16384
	ds_read_b128 v[192:195], v170 offset:17408
	ds_read_b128 v[196:199], v170 offset:18432
	ds_read_b128 v[200:203], v170 offset:19456
	ds_read_b128 v[204:207], v170 offset:20480
	ds_read_b128 v[208:211], v170 offset:21504
	ds_read_b128 v[212:215], v170 offset:22528
	ds_read_b128 v[216:219], v170 offset:23552
	global_load_lds_dwordx4 v[2:3], off
	s_add_i32 m0, s91, 0x2000
	v_lshl_add_u64 v[2:3], s[56:57], 0, v[146:147]
	s_add_u32 s56, s56, 0x100000
	s_addc_u32 s57, s57, 0
	s_add_i32 s91, s78, s63
	global_load_lds_dwordx4 v[2:3], off
	v_lshl_add_u64 v[2:3], s[56:57], 0, v[142:143]
	s_mov_b32 m0, s91
	s_nop 0
	global_load_lds_dwordx4 v[2:3], off
	v_lshl_add_u64 v[2:3], s[56:57], 0, v[146:147]
	s_add_i32 m0, s91, 0x2000
	s_nop 0
	global_load_lds_dwordx4 v[2:3], off
	v_lshl_add_u64 v[2:3], s[42:43], 0, v[140:141]
	s_mov_b32 m0, s64
	s_nop 0
	global_load_lds_dwordx4 v[2:3], off
	v_lshl_add_u64 v[2:3], s[42:43], 0, v[144:145]
	s_mov_b32 m0, s65
	s_nop 0
	global_load_lds_dwordx4 v[2:3], off
	s_waitcnt vmcnt(8)
	s_waitcnt lgkmcnt(0)
	s_setprio 1
	s_barrier
	v_mfma_f32_16x16x32_bf16 v[64:67], v[132:135], v[188:191], 0
	v_mfma_f32_16x16x32_bf16 v[60:63], v[156:159], v[188:191], 0
	v_mfma_f32_16x16x32_bf16 v[56:59], v[132:135], v[196:199], 0
	v_mfma_f32_16x16x32_bf16 v[52:55], v[156:159], v[196:199], 0
	v_mfma_f32_16x16x32_bf16 v[48:51], v[132:135], v[204:207], 0
	v_mfma_f32_16x16x32_bf16 v[44:47], v[156:159], v[204:207], 0
	v_mfma_f32_16x16x32_bf16 v[40:43], v[132:135], v[212:215], 0
	v_mfma_f32_16x16x32_bf16 v[36:39], v[156:159], v[212:215], 0
	v_mfma_f32_16x16x32_bf16 v[64:67], v[136:139], v[192:195], v[64:67]
	v_mfma_f32_16x16x32_bf16 v[60:63], v[160:163], v[192:195], v[60:63]
	v_mfma_f32_16x16x32_bf16 v[56:59], v[136:139], v[200:203], v[56:59]
	v_mfma_f32_16x16x32_bf16 v[52:55], v[160:163], v[200:203], v[52:55]
	v_mfma_f32_16x16x32_bf16 v[48:51], v[136:139], v[208:211], v[48:51]
	v_mfma_f32_16x16x32_bf16 v[44:47], v[160:163], v[208:211], v[44:47]
	v_mfma_f32_16x16x32_bf16 v[40:43], v[136:139], v[216:219], v[40:43]
	v_mfma_f32_16x16x32_bf16 v[36:39], v[160:163], v[216:219], v[36:39]
	v_mfma_f32_16x16x32_bf16 v[32:35], v[172:175], v[188:191], 0
	v_mfma_f32_16x16x32_bf16 v[28:31], v[180:183], v[188:191], 0
	v_mfma_f32_16x16x32_bf16 v[24:27], v[172:175], v[196:199], 0
	v_mfma_f32_16x16x32_bf16 v[20:23], v[180:183], v[196:199], 0
	v_mfma_f32_16x16x32_bf16 v[16:19], v[172:175], v[204:207], 0
	v_mfma_f32_16x16x32_bf16 v[12:15], v[180:183], v[204:207], 0
	v_mfma_f32_16x16x32_bf16 v[8:11], v[172:175], v[212:215], 0
	v_mfma_f32_16x16x32_bf16 v[2:5], v[180:183], v[212:215], 0
	v_mfma_f32_16x16x32_bf16 v[32:35], v[176:179], v[192:195], v[32:35]
	v_mfma_f32_16x16x32_bf16 v[28:31], v[184:187], v[192:195], v[28:31]
	v_mfma_f32_16x16x32_bf16 v[24:27], v[176:179], v[200:203], v[24:27]
	v_mfma_f32_16x16x32_bf16 v[20:23], v[184:187], v[200:203], v[20:23]
	v_mfma_f32_16x16x32_bf16 v[16:19], v[176:179], v[208:211], v[16:19]
	v_mfma_f32_16x16x32_bf16 v[12:15], v[184:187], v[208:211], v[12:15]
	v_mfma_f32_16x16x32_bf16 v[8:11], v[176:179], v[216:219], v[8:11]
	v_mfma_f32_16x16x32_bf16 v[2:5], v[184:187], v[216:219], v[2:5]
	s_barrier
	s_branch .Lmid_k966

; #define PG8_STAGE(bufoff, gbase, voff) do { _Pragma("unroll") for (int _i = 0; _i < 2; ++_i) \
;         __builtin_amdgcn_global_load_lds((const unsigned*)((const char*)(gbase) + (voff)[_i]), (PG8_LAS unsigned*)(lds + (bufoff) + ldsw + _i * 8192), 16, 0, 0); } while (0)
; #define PG8_LDA(dst, b, h) do { _Pragma("unroll") for (int m = 0; m < 4; ++m) _Pragma("unroll") for (int k = 0; k < 2; ++k) dst[m][k] = *(const PG8_LAS bf16x8*)(lds + PG8_SA(b, h) + aoff + m * 2048 + k * 1024); } while (0)
; #define PG8_LDB(dst, b, h) do { _Pragma("unroll") for (int n = 0; n < 2; ++n) _Pragma("unroll") for (int k = 0; k < 2; ++k) dst[n][k] = *(const PG8_LAS bf16x8*)(lds + PG8_SB(b, h) + boff + n * 2048 + k * 1024); } while (0)
; #define PG8_WAIT_V(n) asm volatile("s_waitcnt vmcnt(" #n ")" ::: "memory")
; #define PG8_WAIT_L(n) asm volatile("s_waitcnt lgkmcnt(" #n ")" ::: "memory")
; #define PG8_BAR __builtin_amdgcn_s_barrier()
; #define PG8_SCHED __builtin_amdgcn_sched_barrier(0)
; template <class Epi, class Sched, bool ALIGN_EPI = false, bool SP2 = false, bool F8 = false>
; __device__ __forceinline__ void gemm_phase(PG8_LAS unsigned char* lds, const int K, const Sched& S, const Epi& E, const int wave) {
;     ...
;             PG8_LDB(B0, 1, 0); PG8_LDB(B1, 1, 1); PG8_SCHED; PG8_LDA(At, 1, 0); PG8_STAGE(PG8_SA(0, 1), a2 + hstep, voffA);
;             PG8_WAIT_V(8); PG8_WAIT_L(0); PG8_BAR; PG8_MMA(0, 0, At, B0); PG8_MMA(0, 1, At, B1); PG8_BAR; PG8_SCHED;
.Lmid_k966:
	s_setprio 0
	s_add_i32 s56, 0, 0x18000
	v_add_u32_e32 v1, s56, v168
	s_add_i32 s57, 0, 0x1c000
	ds_read_b128 v[132:135], v1
	ds_read_b128 v[136:139], v1 offset:1024
	ds_read_b128 v[156:159], v1 offset:2048
	ds_read_b128 v[160:163], v1 offset:3072
	v_add_u32_e32 v1, s57, v168
	ds_read_b128 v[172:175], v1
	ds_read_b128 v[176:179], v1 offset:1024
	ds_read_b128 v[180:183], v1 offset:2048
	ds_read_b128 v[184:187], v1 offset:3072
	s_add_u32 s42, s42, 0x100000
	s_addc_u32 s43, s43, 0
	s_mov_b32 m0, s66
	v_lshl_add_u64 v[6:7], s[42:43], 0, v[140:141]
	ds_read_b128 v[188:191], v170 offset:32768
	ds_read_b128 v[192:195], v170 offset:33792
	ds_read_b128 v[196:199], v170 offset:34816
	ds_read_b128 v[200:203], v170 offset:35840
	ds_read_b128 v[204:207], v170 offset:36864
	ds_read_b128 v[208:211], v170 offset:37888
	ds_read_b128 v[212:215], v170 offset:38912
	ds_read_b128 v[216:219], v170 offset:39936
	global_load_lds_dwordx4 v[6:7], off
	v_lshl_add_u64 v[6:7], s[42:43], 0, v[144:145]
	s_mov_b32 m0, s67
	s_nop 0
	global_load_lds_dwordx4 v[6:7], off
	s_waitcnt vmcnt(8)
	s_waitcnt lgkmcnt(0)
	s_setprio 1
	s_barrier
	v_mfma_f32_16x16x32_bf16 v[128:131], v[132:135], v[188:191], v[128:131]
	v_mfma_f32_16x16x32_bf16 v[124:127], v[156:159], v[188:191], v[124:127]
	v_mfma_f32_16x16x32_bf16 v[120:123], v[132:135], v[196:199], v[120:123]
	v_mfma_f32_16x16x32_bf16 v[116:119], v[156:159], v[196:199], v[116:119]
	v_mfma_f32_16x16x32_bf16 v[112:115], v[132:135], v[204:207], v[112:115]
	v_mfma_f32_16x16x32_bf16 v[108:111], v[156:159], v[204:207], v[108:111]
	v_mfma_f32_16x16x32_bf16 v[104:107], v[132:135], v[212:215], v[104:107]
	v_mfma_f32_16x16x32_bf16 v[100:103], v[156:159], v[212:215], v[100:103]
	v_mfma_f32_16x16x32_bf16 v[128:131], v[136:139], v[192:195], v[128:131]
	v_mfma_f32_16x16x32_bf16 v[124:127], v[160:163], v[192:195], v[124:127]
	v_mfma_f32_16x16x32_bf16 v[120:123], v[136:139], v[200:203], v[120:123]
	v_mfma_f32_16x16x32_bf16 v[116:119], v[160:163], v[200:203], v[116:119]
	v_mfma_f32_16x16x32_bf16 v[112:115], v[136:139], v[208:211], v[112:115]
	v_mfma_f32_16x16x32_bf16 v[108:111], v[160:163], v[208:211], v[108:111]
	v_mfma_f32_16x16x32_bf16 v[104:107], v[136:139], v[216:219], v[104:107]
	v_mfma_f32_16x16x32_bf16 v[100:103], v[160:163], v[216:219], v[100:103]
	v_mfma_f32_16x16x32_bf16 v[96:99], v[172:175], v[188:191], v[96:99]
	v_mfma_f32_16x16x32_bf16 v[92:95], v[180:183], v[188:191], v[92:95]
	v_mfma_f32_16x16x32_bf16 v[88:91], v[172:175], v[196:199], v[88:91]
	v_mfma_f32_16x16x32_bf16 v[84:87], v[180:183], v[196:199], v[84:87]
	v_mfma_f32_16x16x32_bf16 v[80:83], v[172:175], v[204:207], v[80:83]
	v_mfma_f32_16x16x32_bf16 v[76:79], v[180:183], v[204:207], v[76:79]
	v_mfma_f32_16x16x32_bf16 v[72:75], v[172:175], v[212:215], v[72:75]
	v_mfma_f32_16x16x32_bf16 v[68:71], v[180:183], v[212:215], v[68:71]
	v_mfma_f32_16x16x32_bf16 v[96:99], v[176:179], v[192:195], v[96:99]
	v_mfma_f32_16x16x32_bf16 v[92:95], v[184:187], v[192:195], v[92:95]
	v_mfma_f32_16x16x32_bf16 v[88:91], v[176:179], v[200:203], v[88:91]
	v_mfma_f32_16x16x32_bf16 v[84:87], v[184:187], v[200:203], v[84:87]
	v_mfma_f32_16x16x32_bf16 v[80:83], v[176:179], v[208:211], v[80:83]
	v_mfma_f32_16x16x32_bf16 v[76:79], v[184:187], v[208:211], v[76:79]
	v_mfma_f32_16x16x32_bf16 v[72:75], v[176:179], v[216:219], v[72:75]
	v_mfma_f32_16x16x32_bf16 v[68:71], v[184:187], v[216:219], v[68:71]
	s_barrier
; #define PG8_STAGE(bufoff, gbase, voff) do { _Pragma("unroll") for (int _i = 0; _i < 2; ++_i) \
;         __builtin_amdgcn_global_load_lds((const unsigned*)((const char*)(gbase) + (voff)[_i]), (PG8_LAS unsigned*)(lds + (bufoff) + ldsw + _i * 8192), 16, 0, 0); } while (0)
; #define PG8_LDA(dst, b, h) do { _Pragma("unroll") for (int m = 0; m < 4; ++m) _Pragma("unroll") for (int k = 0; k < 2; ++k) dst[m][k] = *(const PG8_LAS bf16x8*)(lds + PG8_SA(b, h) + aoff + m * 2048 + k * 1024); } while (0)
; #define PG8_WAIT_V(n) asm volatile("s_waitcnt vmcnt(" #n ")" ::: "memory")
; #define PG8_WAIT_L(n) asm volatile("s_waitcnt lgkmcnt(" #n ")" ::: "memory")
; #define PG8_BAR __builtin_amdgcn_s_barrier()
; #define PG8_SCHED __builtin_amdgcn_sched_barrier(0)
; template <class Epi, class Sched, bool ALIGN_EPI = false, bool SP2 = false, bool F8 = false>
; __device__ __forceinline__ void gemm_phase(PG8_LAS unsigned char* lds, const int K, const Sched& S, const Epi& E, const int wave) {
;     ...
;             PG8_LDA(At, 1, 1); PG8_STAGE(PG8_SB(1, 0), b3, voffB); PG8_STAGE(PG8_SB(1, 1), b3 + hstep, voffB); PG8_STAGE(PG8_SA(1, 0), a3, voffA);
;             PG8_WAIT_V(8); PG8_WAIT_L(0); PG8_BAR; PG8_MMA(1, 0, At, B0); PG8_MMA(1, 1, At, B1); PG8_BAR; PG8_SCHED;
	s_setprio 0
	s_add_i32 s42, s56, s63
	v_lshl_add_u64 v[6:7], s[40:41], 0, v[142:143]
	s_mov_b32 m0, s42
	ds_read_b128 v[188:191], v170 offset:49152
	ds_read_b128 v[192:195], v170 offset:50176
	ds_read_b128 v[196:199], v170 offset:51200
	ds_read_b128 v[200:203], v170 offset:52224
	ds_read_b128 v[204:207], v170 offset:53248
	ds_read_b128 v[208:211], v170 offset:54272
	ds_read_b128 v[212:215], v170 offset:55296
	ds_read_b128 v[216:219], v170 offset:56320
	global_load_lds_dwordx4 v[6:7], off
	s_add_i32 m0, s42, 0x2000
	v_lshl_add_u64 v[6:7], s[40:41], 0, v[146:147]
	s_add_u32 s40, s40, 0x100000
	s_addc_u32 s41, s41, 0
	s_add_i32 s42, s57, s63
	global_load_lds_dwordx4 v[6:7], off
	v_lshl_add_u64 v[6:7], s[40:41], 0, v[142:143]
	s_mov_b32 m0, s42
	s_nop 0
	global_load_lds_dwordx4 v[6:7], off
	v_lshl_add_u64 v[6:7], s[40:41], 0, v[146:147]
	s_add_i32 m0, s42, 0x2000
	s_nop 0
	global_load_lds_dwordx4 v[6:7], off
	v_lshl_add_u64 v[6:7], s[8:9], 0, v[140:141]
	s_mov_b32 m0, s74
	s_nop 0
	global_load_lds_dwordx4 v[6:7], off
	v_lshl_add_u64 v[6:7], s[8:9], 0, v[144:145]
	s_mov_b32 m0, s76
	s_nop 0
	global_load_lds_dwordx4 v[6:7], off
	s_waitcnt vmcnt(8)
	s_waitcnt lgkmcnt(0)
	s_setprio 1
	s_barrier
	v_mfma_f32_16x16x32_bf16 v[64:67], v[132:135], v[188:191], v[64:67]
	v_mfma_f32_16x16x32_bf16 v[60:63], v[156:159], v[188:191], v[60:63]
	v_mfma_f32_16x16x32_bf16 v[56:59], v[132:135], v[196:199], v[56:59]
	v_mfma_f32_16x16x32_bf16 v[52:55], v[156:159], v[196:199], v[52:55]
	v_mfma_f32_16x16x32_bf16 v[48:51], v[132:135], v[204:207], v[48:51]
	v_mfma_f32_16x16x32_bf16 v[44:47], v[156:159], v[204:207], v[44:47]
	v_mfma_f32_16x16x32_bf16 v[40:43], v[132:135], v[212:215], v[40:43]
	v_mfma_f32_16x16x32_bf16 v[36:39], v[156:159], v[212:215], v[36:39]
	v_mfma_f32_16x16x32_bf16 v[64:67], v[136:139], v[192:195], v[64:67]
	v_mfma_f32_16x16x32_bf16 v[60:63], v[160:163], v[192:195], v[60:63]
	v_mfma_f32_16x16x32_bf16 v[56:59], v[136:139], v[200:203], v[56:59]
	v_mfma_f32_16x16x32_bf16 v[52:55], v[160:163], v[200:203], v[52:55]
	v_mfma_f32_16x16x32_bf16 v[48:51], v[136:139], v[208:211], v[48:51]
	v_mfma_f32_16x16x32_bf16 v[44:47], v[160:163], v[208:211], v[44:47]
	v_mfma_f32_16x16x32_bf16 v[40:43], v[136:139], v[216:219], v[40:43]
	v_mfma_f32_16x16x32_bf16 v[36:39], v[160:163], v[216:219], v[36:39]
	v_mfma_f32_16x16x32_bf16 v[32:35], v[172:175], v[188:191], v[32:35]
	v_mfma_f32_16x16x32_bf16 v[28:31], v[180:183], v[188:191], v[28:31]
	v_mfma_f32_16x16x32_bf16 v[24:27], v[172:175], v[196:199], v[24:27]
	v_mfma_f32_16x16x32_bf16 v[20:23], v[180:183], v[196:199], v[20:23]
	v_mfma_f32_16x16x32_bf16 v[16:19], v[172:175], v[204:207], v[16:19]
	v_mfma_f32_16x16x32_bf16 v[12:15], v[180:183], v[204:207], v[12:15]
	v_mfma_f32_16x16x32_bf16 v[6:9], v[172:175], v[212:215], v[8:11]
	v_mfma_f32_16x16x32_bf16 v[2:5], v[180:183], v[212:215], v[2:5]
	v_mfma_f32_16x16x32_bf16 v[32:35], v[176:179], v[192:195], v[32:35]
	v_mfma_f32_16x16x32_bf16 v[28:31], v[184:187], v[192:195], v[28:31]
	v_mfma_f32_16x16x32_bf16 v[24:27], v[176:179], v[200:203], v[24:27]
	v_mfma_f32_16x16x32_bf16 v[20:23], v[184:187], v[200:203], v[20:23]
	v_mfma_f32_16x16x32_bf16 v[16:19], v[176:179], v[208:211], v[16:19]
	v_mfma_f32_16x16x32_bf16 v[12:15], v[184:187], v[208:211], v[12:15]
	v_mfma_f32_16x16x32_bf16 v[8:11], v[176:179], v[216:219], v[6:9]
	v_mfma_f32_16x16x32_bf16 v[4:7], v[184:187], v[216:219], v[2:5]
	s_barrier
	s_setprio 0
	s_add_u32 s86, s86, 0x100
	s_addc_u32 s87, s87, 0
	s_add_u32 s88, s88, 0x100
	s_addc_u32 s89, s89, 0
	s_add_u32 s6, s6, 0x100
	s_addc_u32 s7, s7, 0
	s_cmp_ge_i32 s90, s62
	s_mov_b32 s8, s90
	s_cbranch_scc0 .LBB0_966

; template <class Epi, class Sched, bool ALIGN_EPI = false, bool SP2 = false, bool F8 = false>
; __device__ __forceinline__ void gemm_phase(PG8_LAS unsigned char* lds, const int K, const Sched& S, const Epi& E, const int wave) {
;     ...
; #pragma unroll
;         for (int a = 0; a < 2; ++a)
; #pragma unroll
;             for (int b = 0; b < 2; ++b)
; #pragma unroll
;                 for (int m = 0; m < 4; ++m)
; #pragma unroll
;                     for (int n = 0; n < 2; ++n) acc[a][b][m][n] = (f32x4){0.f, 0.f, 0.f, 0.f};
;         cur = nxt; cA = nA; cB = nB; ++ui;
.LBB0_1235:
	s_mov_b32 s49, s22
	s_mov_b32 s8, s24
	s_mov_b64 s[10:11], s[28:29]
	s_mov_b64 s[12:13], s[26:27]
	s_mov_b32 s56, s62

; #define PG8_STAGE(bufoff, gbase, voff) do { _Pragma("unroll") for (int _i = 0; _i < 2; ++_i) \
;         __builtin_amdgcn_global_load_lds((const unsigned*)((const char*)(gbase) + (voff)[_i]), (PG8_LAS unsigned*)(lds + (bufoff) + ldsw + _i * 8192), 16, 0, 0); } while (0)
; #define PG8_LDA(dst, b, h) do { _Pragma("unroll") for (int m = 0; m < 4; ++m) _Pragma("unroll") for (int k = 0; k < 2; ++k) dst[m][k] = *(const PG8_LAS bf16x8*)(lds + PG8_SA(b, h) + aoff + m * 2048 + k * 1024); } while (0)
; #define PG8_LDB(dst, b, h) do { _Pragma("unroll") for (int n = 0; n < 2; ++n) _Pragma("unroll") for (int k = 0; k < 2; ++k) dst[n][k] = *(const PG8_LAS bf16x8*)(lds + PG8_SB(b, h) + boff + n * 2048 + k * 1024); } while (0)
; #define PG8_WAIT_V(n) asm volatile("s_waitcnt vmcnt(" #n ")" ::: "memory")
; #define PG8_WAIT_L(n) asm volatile("s_waitcnt lgkmcnt(" #n ")" ::: "memory")
; #define PG8_BAR __builtin_amdgcn_s_barrier()
; #define PG8_SCHED __builtin_amdgcn_sched_barrier(0)
; template <class Epi, class Sched, bool ALIGN_EPI = false, bool SP2 = false, bool F8 = false>
; __device__ __forceinline__ void gemm_phase(PG8_LAS unsigned char* lds, const int K, const Sched& S, const Epi& E, const int wave) {
;     ...
;         for (int t = 0; t < nt; t += 2) {
;             const bool last = (t == nt - 2);
;             const char* a1 = cA + (size_t)(t + 1) * kstep;
;             const char* a2 = last ? nA : cA + (size_t)(t + 2) * kstep; const char* b2 = last ? nB : cB + (size_t)(t + 2) * kstep;
;             const char* a3 = a2 + kstep; const char* b3 = b2 + kstep;
;             asm volatile("" : "+s"(a1), "+s"(a2), "+s"(b2), "+s"(a3), "+s"(b3));
;             if (last && has_next) S.a_ready(nxt);
;             if constexpr (Epi::KHOOK) { if (cur.prob == 2 ? (t == 16) : (t == 32 || t == 48)) { if (wr == 0) PG8_BAR;
;                 E.khook(acc, cur, (cur.prob == 2 || t == 48) ? 1 : 0, wr, wc, fr, fq); if (wr == 1) PG8_BAR; } }
;             if constexpr (SP2) {
;             PG8_LDB(B0, 0, 0); PG8_LDB(B1, 0, 1); PG8_SCHED; PG8_LDA(At, 0, 0); PG8_STAGE(PG8_SA(1, 1), a1 + hstep, voffA);
;             PG8_WAIT_V(8); PG8_WAIT_L(0); PG8_BAR; PG8_MMA(0, 0, At, B0); PG8_MMA(0, 1, At, B1); PG8_BAR; PG8_SCHED;
.LBB0_1239:
	s_mov_b32 s23, -2
	s_mov_b64 s[38:39], 0x100
	s_add_u32 s25, s10, s38
	s_addc_u32 s40, s11, s39
	s_add_u32 s64, s25, 0xffffff80
	s_addc_u32 s65, s40, -1
	s_add_u32 s41, s12, s38
	s_addc_u32 s42, s13, s39
	s_cmp_eq_u32 s23, 60
	s_cselect_b32 s44, s30, s25
	s_cselect_b32 s45, s31, s40
	s_cselect_b32 s53, s37, s42
	s_cselect_b32 s52, s36, s41
	s_add_u32 s40, s44, 0x80
	s_addc_u32 s41, s45, 0
	s_add_u32 s42, s52, 0x80
	s_addc_u32 s43, s53, 0
	v_add_u32_e32 v149, s59, v146
	ds_read_b128 v[140:143], v149
	ds_read_b128 v[150:153], v149 offset:1024
	ds_read_b128 v[154:157], v149 offset:2048
	ds_read_b128 v[158:161], v149 offset:3072
	v_add_u32_e32 v149, s60, v146
	ds_read_b128 v[162:165], v149
	ds_read_b128 v[166:169], v149 offset:1024
	ds_read_b128 v[170:173], v149 offset:2048
	ds_read_b128 v[174:177], v149 offset:3072
	s_add_u32 s64, s64, 0x100000
	s_addc_u32 s65, s65, 0
	v_lshl_add_u64 v[210:211], s[64:65], 0, v[134:135]
	s_add_i32 m0, s9, 0xc000
	ds_read_b128 v[178:181], v148
	ds_read_b128 v[182:185], v148 offset:1024
	ds_read_b128 v[186:189], v148 offset:2048
	ds_read_b128 v[190:193], v148 offset:3072
	ds_read_b128 v[194:197], v148 offset:4096
	ds_read_b128 v[198:201], v148 offset:5120
	ds_read_b128 v[202:205], v148 offset:6144
	ds_read_b128 v[206:209], v148 offset:7168
	global_load_lds_dwordx4 v[210:211], off
	v_lshl_add_u64 v[210:211], s[64:65], 0, v[130:131]
	s_add_i32 m0, s9, 0xe000
	s_nop 0
	global_load_lds_dwordx4 v[210:211], off
	s_waitcnt vmcnt(8)
	s_waitcnt lgkmcnt(0)
	s_setprio 1
	s_barrier
	v_mfma_f32_16x16x32_bf16 v[124:127], v[140:143], v[178:181], 0
	v_mfma_f32_16x16x32_bf16 v[120:123], v[154:157], v[178:181], 0
	v_mfma_f32_16x16x32_bf16 v[116:119], v[140:143], v[186:189], 0
	v_mfma_f32_16x16x32_bf16 v[112:115], v[154:157], v[186:189], 0
	v_mfma_f32_16x16x32_bf16 v[108:111], v[140:143], v[194:197], 0
	v_mfma_f32_16x16x32_bf16 v[104:107], v[154:157], v[194:197], 0
	v_mfma_f32_16x16x32_bf16 v[100:103], v[140:143], v[202:205], 0
	v_mfma_f32_16x16x32_bf16 v[96:99], v[154:157], v[202:205], 0
	v_mfma_f32_16x16x32_bf16 v[124:127], v[150:153], v[182:185], v[124:127]
	v_mfma_f32_16x16x32_bf16 v[120:123], v[158:161], v[182:185], v[120:123]
	v_mfma_f32_16x16x32_bf16 v[116:119], v[150:153], v[190:193], v[116:119]
	v_mfma_f32_16x16x32_bf16 v[112:115], v[158:161], v[190:193], v[112:115]
	v_mfma_f32_16x16x32_bf16 v[108:111], v[150:153], v[198:201], v[108:111]
	v_mfma_f32_16x16x32_bf16 v[104:107], v[158:161], v[198:201], v[104:107]
	v_mfma_f32_16x16x32_bf16 v[100:103], v[150:153], v[206:209], v[100:103]
	v_mfma_f32_16x16x32_bf16 v[96:99], v[158:161], v[206:209], v[96:99]
	v_mfma_f32_16x16x32_bf16 v[92:95], v[162:165], v[178:181], 0
	v_mfma_f32_16x16x32_bf16 v[88:91], v[170:173], v[178:181], 0
	v_mfma_f32_16x16x32_bf16 v[84:87], v[162:165], v[186:189], 0
	v_mfma_f32_16x16x32_bf16 v[80:83], v[170:173], v[186:189], 0
	v_mfma_f32_16x16x32_bf16 v[76:79], v[162:165], v[194:197], 0
	v_mfma_f32_16x16x32_bf16 v[72:75], v[170:173], v[194:197], 0
	v_mfma_f32_16x16x32_bf16 v[68:71], v[162:165], v[202:205], 0
	v_mfma_f32_16x16x32_bf16 v[64:67], v[170:173], v[202:205], 0
	v_mfma_f32_16x16x32_bf16 v[92:95], v[166:169], v[182:185], v[92:95]
	v_mfma_f32_16x16x32_bf16 v[88:91], v[174:177], v[182:185], v[88:91]
	v_mfma_f32_16x16x32_bf16 v[84:87], v[166:169], v[190:193], v[84:87]
	v_mfma_f32_16x16x32_bf16 v[80:83], v[174:177], v[190:193], v[80:83]
	v_mfma_f32_16x16x32_bf16 v[76:79], v[166:169], v[198:201], v[76:79]
	v_mfma_f32_16x16x32_bf16 v[72:75], v[174:177], v[198:201], v[72:75]
	v_mfma_f32_16x16x32_bf16 v[68:71], v[166:169], v[206:209], v[68:71]
	v_mfma_f32_16x16x32_bf16 v[64:67], v[174:177], v[206:209], v[64:67]
	s_barrier
; #define PG8_STAGE(bufoff, gbase, voff) do { _Pragma("unroll") for (int _i = 0; _i < 2; ++_i) \
;         __builtin_amdgcn_global_load_lds((const unsigned*)((const char*)(gbase) + (voff)[_i]), (PG8_LAS unsigned*)(lds + (bufoff) + ldsw + _i * 8192), 16, 0, 0); } while (0)
; #define PG8_LDA(dst, b, h) do { _Pragma("unroll") for (int m = 0; m < 4; ++m) _Pragma("unroll") for (int k = 0; k < 2; ++k) dst[m][k] = *(const PG8_LAS bf16x8*)(lds + PG8_SA(b, h) + aoff + m * 2048 + k * 1024); } while (0)
; #define PG8_WAIT_V(n) asm volatile("s_waitcnt vmcnt(" #n ")" ::: "memory")
; #define PG8_WAIT_L(n) asm volatile("s_waitcnt lgkmcnt(" #n ")" ::: "memory")
; #define PG8_BAR __builtin_amdgcn_s_barrier()
; #define PG8_SCHED __builtin_amdgcn_sched_barrier(0)
; template <class Epi, class Sched, bool ALIGN_EPI = false, bool SP2 = false, bool F8 = false>
; __device__ __forceinline__ void gemm_phase(PG8_LAS unsigned char* lds, const int K, const Sched& S, const Epi& E, const int wave) {
;     ...
;             PG8_LDA(At, 0, 1); PG8_STAGE(PG8_SB(0, 0), b2, voffB); PG8_STAGE(PG8_SB(0, 1), b2 + hstep, voffB); PG8_STAGE(PG8_SA(0, 0), a2, voffA);
;             PG8_WAIT_V(8); PG8_WAIT_L(0); PG8_BAR; PG8_MMA(1, 0, At, B0); PG8_MMA(1, 1, At, B1); PG8_BAR; PG8_SCHED;
	s_setprio 0
	s_add_i32 s25, s59, s48
	v_lshl_add_u64 v[210:211], s[52:53], 0, v[132:133]
	s_mov_b32 m0, s25
	ds_read_b128 v[178:181], v148 offset:16384
	ds_read_b128 v[182:185], v148 offset:17408
	ds_read_b128 v[186:189], v148 offset:18432
	ds_read_b128 v[190:193], v148 offset:19456
	ds_read_b128 v[194:197], v148 offset:20480
	ds_read_b128 v[198:201], v148 offset:21504
	ds_read_b128 v[202:205], v148 offset:22528
	ds_read_b128 v[206:209], v148 offset:23552
	global_load_lds_dwordx4 v[210:211], off
	s_add_i32 m0, s25, 0x2000
	v_lshl_add_u64 v[210:211], s[52:53], 0, v[128:129]
	s_add_u32 s52, s52, 0x100000
	s_addc_u32 s53, s53, 0
	s_add_i32 s25, s60, s48
	global_load_lds_dwordx4 v[210:211], off
	v_lshl_add_u64 v[210:211], s[52:53], 0, v[132:133]
	s_mov_b32 m0, s25
	s_nop 0
	global_load_lds_dwordx4 v[210:211], off
	v_lshl_add_u64 v[210:211], s[52:53], 0, v[128:129]
	s_add_i32 m0, s25, 0x2000
	s_nop 0
	global_load_lds_dwordx4 v[210:211], off
	v_lshl_add_u64 v[210:211], s[44:45], 0, v[134:135]
	s_mov_b32 m0, s9
	s_nop 0
	global_load_lds_dwordx4 v[210:211], off
	v_lshl_add_u64 v[210:211], s[44:45], 0, v[130:131]
	s_mov_b32 m0, s50
	s_nop 0
	global_load_lds_dwordx4 v[210:211], off
	s_waitcnt vmcnt(8)
	s_waitcnt lgkmcnt(0)
	s_setprio 1
	s_barrier
	v_mfma_f32_16x16x32_bf16 v[60:63], v[140:143], v[178:181], 0
	v_mfma_f32_16x16x32_bf16 v[56:59], v[154:157], v[178:181], 0
	v_mfma_f32_16x16x32_bf16 v[52:55], v[140:143], v[186:189], 0
	v_mfma_f32_16x16x32_bf16 v[48:51], v[154:157], v[186:189], 0
	v_mfma_f32_16x16x32_bf16 v[44:47], v[140:143], v[194:197], 0
	v_mfma_f32_16x16x32_bf16 v[40:43], v[154:157], v[194:197], 0
	v_mfma_f32_16x16x32_bf16 v[36:39], v[140:143], v[202:205], 0
	v_mfma_f32_16x16x32_bf16 v[32:35], v[154:157], v[202:205], 0
	v_mfma_f32_16x16x32_bf16 v[60:63], v[150:153], v[182:185], v[60:63]
	v_mfma_f32_16x16x32_bf16 v[56:59], v[158:161], v[182:185], v[56:59]
	v_mfma_f32_16x16x32_bf16 v[52:55], v[150:153], v[190:193], v[52:55]
	v_mfma_f32_16x16x32_bf16 v[48:51], v[158:161], v[190:193], v[48:51]
	v_mfma_f32_16x16x32_bf16 v[44:47], v[150:153], v[198:201], v[44:47]
	v_mfma_f32_16x16x32_bf16 v[40:43], v[158:161], v[198:201], v[40:43]
	v_mfma_f32_16x16x32_bf16 v[36:39], v[150:153], v[206:209], v[36:39]
	v_mfma_f32_16x16x32_bf16 v[32:35], v[158:161], v[206:209], v[32:35]
	v_mfma_f32_16x16x32_bf16 v[28:31], v[162:165], v[178:181], 0
	v_mfma_f32_16x16x32_bf16 v[24:27], v[170:173], v[178:181], 0
	v_mfma_f32_16x16x32_bf16 v[20:23], v[162:165], v[186:189], 0
	v_mfma_f32_16x16x32_bf16 v[16:19], v[170:173], v[186:189], 0
	v_mfma_f32_16x16x32_bf16 v[12:15], v[162:165], v[194:197], 0
	v_mfma_f32_16x16x32_bf16 v[8:11], v[170:173], v[194:197], 0
	v_mfma_f32_16x16x32_bf16 v[4:7], v[162:165], v[202:205], 0
	v_mfma_f32_16x16x32_bf16 v[0:3], v[170:173], v[202:205], 0
	v_mfma_f32_16x16x32_bf16 v[28:31], v[166:169], v[182:185], v[28:31]
	v_mfma_f32_16x16x32_bf16 v[24:27], v[174:177], v[182:185], v[24:27]
	v_mfma_f32_16x16x32_bf16 v[20:23], v[166:169], v[190:193], v[20:23]
	v_mfma_f32_16x16x32_bf16 v[16:19], v[174:177], v[190:193], v[16:19]
	v_mfma_f32_16x16x32_bf16 v[12:15], v[166:169], v[198:201], v[12:15]
	v_mfma_f32_16x16x32_bf16 v[8:11], v[174:177], v[198:201], v[8:11]
	v_mfma_f32_16x16x32_bf16 v[4:7], v[166:169], v[206:209], v[4:7]
	v_mfma_f32_16x16x32_bf16 v[0:3], v[174:177], v[206:209], v[0:3]
	s_barrier
	s_branch .Lmid_k1240

; #define PG8_STAGE(bufoff, gbase, voff) do { _Pragma("unroll") for (int _i = 0; _i < 2; ++_i) \
;         __builtin_amdgcn_global_load_lds((const unsigned*)((const char*)(gbase) + (voff)[_i]), (PG8_LAS unsigned*)(lds + (bufoff) + ldsw + _i * 8192), 16, 0, 0); } while (0)
; #define PG8_LDA(dst, b, h) do { _Pragma("unroll") for (int m = 0; m < 4; ++m) _Pragma("unroll") for (int k = 0; k < 2; ++k) dst[m][k] = *(const PG8_LAS bf16x8*)(lds + PG8_SA(b, h) + aoff + m * 2048 + k * 1024); } while (0)
; #define PG8_LDB(dst, b, h) do { _Pragma("unroll") for (int n = 0; n < 2; ++n) _Pragma("unroll") for (int k = 0; k < 2; ++k) dst[n][k] = *(const PG8_LAS bf16x8*)(lds + PG8_SB(b, h) + boff + n * 2048 + k * 1024); } while (0)
; #define PG8_WAIT_V(n) asm volatile("s_waitcnt vmcnt(" #n ")" ::: "memory")
; #define PG8_WAIT_L(n) asm volatile("s_waitcnt lgkmcnt(" #n ")" ::: "memory")
; #define PG8_BAR __builtin_amdgcn_s_barrier()
; #define PG8_SCHED __builtin_amdgcn_sched_barrier(0)
; template <class Epi, class Sched, bool ALIGN_EPI = false, bool SP2 = false, bool F8 = false>
; __device__ __forceinline__ void gemm_phase(PG8_LAS unsigned char* lds, const int K, const Sched& S, const Epi& E, const int wave) {
;     ...
;             PG8_LDB(B0, 1, 0); PG8_LDB(B1, 1, 1); PG8_SCHED; PG8_LDA(At, 1, 0); PG8_STAGE(PG8_SA(0, 1), a2 + hstep, voffA);
;             PG8_WAIT_V(8); PG8_WAIT_L(0); PG8_BAR; PG8_MMA(0, 0, At, B0); PG8_MMA(0, 1, At, B1); PG8_BAR; PG8_SCHED;
.Lmid_k1240:
	s_setprio 0
	s_add_i32 s25, 0, 0x18000
	v_add_u32_e32 v149, s25, v146
	s_add_i32 s52, 0, 0x1c000
	ds_read_b128 v[140:143], v149
	ds_read_b128 v[150:153], v149 offset:1024
	ds_read_b128 v[154:157], v149 offset:2048
	ds_read_b128 v[158:161], v149 offset:3072
	v_add_u32_e32 v149, s52, v146
	ds_read_b128 v[162:165], v149
	ds_read_b128 v[166:169], v149 offset:1024
	ds_read_b128 v[170:173], v149 offset:2048
	ds_read_b128 v[174:177], v149 offset:3072
	s_add_u32 s44, s44, 0x100000
	s_addc_u32 s45, s45, 0
	s_mov_b32 m0, s51
	v_lshl_add_u64 v[210:211], s[44:45], 0, v[134:135]
	ds_read_b128 v[178:181], v148 offset:32768
	ds_read_b128 v[182:185], v148 offset:33792
	ds_read_b128 v[186:189], v148 offset:34816
	ds_read_b128 v[190:193], v148 offset:35840
	ds_read_b128 v[194:197], v148 offset:36864
	ds_read_b128 v[198:201], v148 offset:37888
	ds_read_b128 v[202:205], v148 offset:38912
	ds_read_b128 v[206:209], v148 offset:39936
	global_load_lds_dwordx4 v[210:211], off
	v_lshl_add_u64 v[210:211], s[44:45], 0, v[130:131]
	s_mov_b32 m0, s54
	s_nop 0
	global_load_lds_dwordx4 v[210:211], off
	s_waitcnt vmcnt(8)
	s_waitcnt lgkmcnt(0)
	s_setprio 1
	s_barrier
	v_mfma_f32_16x16x32_bf16 v[124:127], v[140:143], v[178:181], v[124:127]
	v_mfma_f32_16x16x32_bf16 v[120:123], v[154:157], v[178:181], v[120:123]
	v_mfma_f32_16x16x32_bf16 v[116:119], v[140:143], v[186:189], v[116:119]
	v_mfma_f32_16x16x32_bf16 v[112:115], v[154:157], v[186:189], v[112:115]
	v_mfma_f32_16x16x32_bf16 v[108:111], v[140:143], v[194:197], v[108:111]
	v_mfma_f32_16x16x32_bf16 v[104:107], v[154:157], v[194:197], v[104:107]
	v_mfma_f32_16x16x32_bf16 v[100:103], v[140:143], v[202:205], v[100:103]
	v_mfma_f32_16x16x32_bf16 v[96:99], v[154:157], v[202:205], v[96:99]
	v_mfma_f32_16x16x32_bf16 v[124:127], v[150:153], v[182:185], v[124:127]
	v_mfma_f32_16x16x32_bf16 v[120:123], v[158:161], v[182:185], v[120:123]
	v_mfma_f32_16x16x32_bf16 v[116:119], v[150:153], v[190:193], v[116:119]
	v_mfma_f32_16x16x32_bf16 v[112:115], v[158:161], v[190:193], v[112:115]
	v_mfma_f32_16x16x32_bf16 v[108:111], v[150:153], v[198:201], v[108:111]
	v_mfma_f32_16x16x32_bf16 v[104:107], v[158:161], v[198:201], v[104:107]
	v_mfma_f32_16x16x32_bf16 v[100:103], v[150:153], v[206:209], v[100:103]
	v_mfma_f32_16x16x32_bf16 v[96:99], v[158:161], v[206:209], v[96:99]
	v_mfma_f32_16x16x32_bf16 v[92:95], v[162:165], v[178:181], v[92:95]
	v_mfma_f32_16x16x32_bf16 v[88:91], v[170:173], v[178:181], v[88:91]
	v_mfma_f32_16x16x32_bf16 v[84:87], v[162:165], v[186:189], v[84:87]
	v_mfma_f32_16x16x32_bf16 v[80:83], v[170:173], v[186:189], v[80:83]
	v_mfma_f32_16x16x32_bf16 v[76:79], v[162:165], v[194:197], v[76:79]
	v_mfma_f32_16x16x32_bf16 v[72:75], v[170:173], v[194:197], v[72:75]
	v_mfma_f32_16x16x32_bf16 v[68:71], v[162:165], v[202:205], v[68:71]
	v_mfma_f32_16x16x32_bf16 v[64:67], v[170:173], v[202:205], v[64:67]
	v_mfma_f32_16x16x32_bf16 v[92:95], v[166:169], v[182:185], v[92:95]
	v_mfma_f32_16x16x32_bf16 v[88:91], v[174:177], v[182:185], v[88:91]
	v_mfma_f32_16x16x32_bf16 v[84:87], v[166:169], v[190:193], v[84:87]
	v_mfma_f32_16x16x32_bf16 v[80:83], v[174:177], v[190:193], v[80:83]
	v_mfma_f32_16x16x32_bf16 v[76:79], v[166:169], v[198:201], v[76:79]
	v_mfma_f32_16x16x32_bf16 v[72:75], v[174:177], v[198:201], v[72:75]
	v_mfma_f32_16x16x32_bf16 v[68:71], v[166:169], v[206:209], v[68:71]
	v_mfma_f32_16x16x32_bf16 v[64:67], v[174:177], v[206:209], v[64:67]
	s_barrier
; #define PG8_STAGE(bufoff, gbase, voff) do { _Pragma("unroll") for (int _i = 0; _i < 2; ++_i) \
;         __builtin_amdgcn_global_load_lds((const unsigned*)((const char*)(gbase) + (voff)[_i]), (PG8_LAS unsigned*)(lds + (bufoff) + ldsw + _i * 8192), 16, 0, 0); } while (0)
; #define PG8_LDA(dst, b, h) do { _Pragma("unroll") for (int m = 0; m < 4; ++m) _Pragma("unroll") for (int k = 0; k < 2; ++k) dst[m][k] = *(const PG8_LAS bf16x8*)(lds + PG8_SA(b, h) + aoff + m * 2048 + k * 1024); } while (0)
; #define PG8_WAIT_V(n) asm volatile("s_waitcnt vmcnt(" #n ")" ::: "memory")
; #define PG8_WAIT_L(n) asm volatile("s_waitcnt lgkmcnt(" #n ")" ::: "memory")
; #define PG8_BAR __builtin_amdgcn_s_barrier()
; #define PG8_SCHED __builtin_amdgcn_sched_barrier(0)
; template <class Epi, class Sched, bool ALIGN_EPI = false, bool SP2 = false, bool F8 = false>
; __device__ __forceinline__ void gemm_phase(PG8_LAS unsigned char* lds, const int K, const Sched& S, const Epi& E, const int wave) {
;     ...
;             PG8_LDA(At, 1, 1); PG8_STAGE(PG8_SB(1, 0), b3, voffB); PG8_STAGE(PG8_SB(1, 1), b3 + hstep, voffB); PG8_STAGE(PG8_SA(1, 0), a3, voffA);
;             PG8_WAIT_V(8); PG8_WAIT_L(0); PG8_BAR; PG8_MMA(1, 0, At, B0); PG8_MMA(1, 1, At, B1); PG8_BAR; PG8_SCHED;
;     ...
;         }
;         if constexpr (ALIGN_EPI) { if (wr == 0) PG8_BAR; }
	s_setprio 0
	s_add_i32 s25, s25, s48
	v_lshl_add_u64 v[210:211], s[42:43], 0, v[132:133]
	s_mov_b32 m0, s25
	ds_read_b128 v[178:181], v148 offset:49152
	ds_read_b128 v[182:185], v148 offset:50176
	ds_read_b128 v[186:189], v148 offset:51200
	ds_read_b128 v[190:193], v148 offset:52224
	ds_read_b128 v[194:197], v148 offset:53248
	ds_read_b128 v[198:201], v148 offset:54272
	ds_read_b128 v[202:205], v148 offset:55296
	ds_read_b128 v[206:209], v148 offset:56320
	global_load_lds_dwordx4 v[210:211], off
	s_add_i32 m0, s25, 0x2000
	v_lshl_add_u64 v[210:211], s[42:43], 0, v[128:129]
	s_add_u32 s42, s42, 0x100000
	s_addc_u32 s43, s43, 0
	s_add_i32 s25, s52, s48
	global_load_lds_dwordx4 v[210:211], off
	v_lshl_add_u64 v[210:211], s[42:43], 0, v[132:133]
	s_mov_b32 m0, s25
	s_nop 0
	global_load_lds_dwordx4 v[210:211], off
	v_lshl_add_u64 v[210:211], s[42:43], 0, v[128:129]
	s_add_i32 m0, s25, 0x2000
	s_nop 0
	global_load_lds_dwordx4 v[210:211], off
	v_lshl_add_u64 v[210:211], s[40:41], 0, v[134:135]
	s_mov_b32 m0, s55
	s_nop 0
	global_load_lds_dwordx4 v[210:211], off
	v_lshl_add_u64 v[210:211], s[40:41], 0, v[130:131]
	s_mov_b32 m0, s57
	s_nop 0
	global_load_lds_dwordx4 v[210:211], off
	s_waitcnt vmcnt(8)
	s_waitcnt lgkmcnt(0)
	s_setprio 1
	s_barrier
	v_mfma_f32_16x16x32_bf16 v[60:63], v[140:143], v[178:181], v[60:63]
	v_mfma_f32_16x16x32_bf16 v[56:59], v[154:157], v[178:181], v[56:59]
	v_mfma_f32_16x16x32_bf16 v[52:55], v[140:143], v[186:189], v[52:55]
	v_mfma_f32_16x16x32_bf16 v[48:51], v[154:157], v[186:189], v[48:51]
	v_mfma_f32_16x16x32_bf16 v[44:47], v[140:143], v[194:197], v[44:47]
	v_mfma_f32_16x16x32_bf16 v[40:43], v[154:157], v[194:197], v[40:43]
	v_mfma_f32_16x16x32_bf16 v[36:39], v[140:143], v[202:205], v[36:39]
	v_mfma_f32_16x16x32_bf16 v[32:35], v[154:157], v[202:205], v[32:35]
	v_mfma_f32_16x16x32_bf16 v[60:63], v[150:153], v[182:185], v[60:63]
	v_mfma_f32_16x16x32_bf16 v[56:59], v[158:161], v[182:185], v[56:59]
	v_mfma_f32_16x16x32_bf16 v[52:55], v[150:153], v[190:193], v[52:55]
	v_mfma_f32_16x16x32_bf16 v[48:51], v[158:161], v[190:193], v[48:51]
	v_mfma_f32_16x16x32_bf16 v[44:47], v[150:153], v[198:201], v[44:47]
	v_mfma_f32_16x16x32_bf16 v[40:43], v[158:161], v[198:201], v[40:43]
	v_mfma_f32_16x16x32_bf16 v[36:39], v[150:153], v[206:209], v[36:39]
	v_mfma_f32_16x16x32_bf16 v[32:35], v[158:161], v[206:209], v[32:35]
	v_mfma_f32_16x16x32_bf16 v[28:31], v[162:165], v[178:181], v[28:31]
	v_mfma_f32_16x16x32_bf16 v[24:27], v[170:173], v[178:181], v[24:27]
	v_mfma_f32_16x16x32_bf16 v[20:23], v[162:165], v[186:189], v[20:23]
	v_mfma_f32_16x16x32_bf16 v[16:19], v[170:173], v[186:189], v[16:19]
	v_mfma_f32_16x16x32_bf16 v[12:15], v[162:165], v[194:197], v[12:15]
	v_mfma_f32_16x16x32_bf16 v[8:11], v[170:173], v[194:197], v[8:11]
	v_mfma_f32_16x16x32_bf16 v[4:7], v[162:165], v[202:205], v[4:7]
	v_mfma_f32_16x16x32_bf16 v[0:3], v[170:173], v[202:205], v[0:3]
	v_mfma_f32_16x16x32_bf16 v[28:31], v[166:169], v[182:185], v[28:31]
	v_mfma_f32_16x16x32_bf16 v[24:27], v[174:177], v[182:185], v[24:27]
	v_mfma_f32_16x16x32_bf16 v[20:23], v[166:169], v[190:193], v[20:23]
	v_mfma_f32_16x16x32_bf16 v[16:19], v[174:177], v[190:193], v[16:19]
	v_mfma_f32_16x16x32_bf16 v[12:15], v[166:169], v[198:201], v[12:15]
	v_mfma_f32_16x16x32_bf16 v[8:11], v[174:177], v[198:201], v[8:11]
	v_mfma_f32_16x16x32_bf16 v[4:7], v[166:169], v[206:209], v[4:7]
	v_mfma_f32_16x16x32_bf16 v[0:3], v[174:177], v[206:209], v[0:3]
	s_barrier
	s_setprio 0
	s_add_i32 s23, s23, 2
	s_add_u32 s38, s38, 0x100
	s_addc_u32 s39, s39, 0
	s_cmp_gt_u32 s23, 61
	s_cbranch_scc0 .LBB0_1240
	s_and_b64 vcc, exec, s[18:19]
	s_cbranch_vccz .LBB0_1243
	s_barrier

; #define PG8_STAGE(bufoff, gbase, voff) do { _Pragma("unroll") for (int _i = 0; _i < 2; ++_i) \
;         __builtin_amdgcn_global_load_lds((const unsigned*)((const char*)(gbase) + (voff)[_i]), (PG8_LAS unsigned*)(lds + (bufoff) + ldsw + _i * 8192), 16, 0, 0); } while (0)
; #define PG8_WAIT_V(n) asm volatile("s_waitcnt vmcnt(" #n ")" ::: "memory")
; #define PG8_BAR __builtin_amdgcn_s_barrier()
; template <class Epi, class Sched, bool ALIGN_EPI = false, bool SP2 = false, bool F8 = false>
; __device__ __forceinline__ void gemm_phase(PG8_LAS unsigned char* lds, const int K, const Sched& S, const Epi& E, const int wave) {
;     ...
;     f32x4 acc[2][2][4][2];
; #pragma unroll
;     for (int a = 0; a < 2; ++a)
; #pragma unroll
;         for (int b = 0; b < 2; ++b)
; #pragma unroll
;             for (int m = 0; m < 4; ++m)
; #pragma unroll
;                 for (int n = 0; n < 2; ++n) acc[a][b][m][n] = (f32x4){0.f, 0.f, 0.f, 0.f};
;     ...
;         PG8_STAGE(PG8_SB(0, 0), cB, voffB); PG8_STAGE(PG8_SB(0, 1), cB + hstep, voffB); PG8_STAGE(PG8_SA(0, 0), cA, voffA); PG8_STAGE(PG8_SA(0, 1), cA + hstep, voffA);
;         if (wr == 1) PG8_BAR;
;         PG8_WAIT_V(2); PG8_BAR;
;         PG8_STAGE(PG8_SB(1, 0), cB + kstep, voffB); PG8_STAGE(PG8_SA(1, 0), cA + kstep, voffA); PG8_STAGE(PG8_SB(1, 1), cB + hstep + kstep, voffB);
;         PG8_WAIT_V(6); PG8_BAR;
.LBB0_1318:
	s_add_u32 s18, s34, 0x3d400000
	s_addc_u32 s19, s35, 0
	s_add_u32 s20, s34, 0x10400000
	s_addc_u32 s21, s35, 0
	s_add_u32 s62, s34, 0x20000
	s_mov_b64 s[0:1], 0x80
	s_addc_u32 s63, s35, 0
	s_add_i32 m0, s58, 0x18000
	v_lshl_add_u64 v[8:9], v[8:9], 0, s[0:1]
	s_bfe_u32 s7, s94, 0x20006
	s_waitcnt vmcnt(2)
	s_barrier
	global_load_lds_dwordx4 v[8:9], off
	v_lshl_add_u64 v[6:7], v[6:7], 0, s[0:1]
	s_add_i32 m0, s58, 0x1a000
	s_add_i32 s65, s58, 0x8000
	s_lshl_b32 s8, s6, 13
	s_lshl_b32 s9, s7, 12
	global_load_lds_dwordx4 v[6:7], off
	v_lshl_add_u64 v[2:3], v[2:3], 0, s[0:1]
	s_mov_b32 m0, s65
	s_add_i32 s66, s58, 0xa000
	global_load_lds_dwordx4 v[2:3], off
	v_lshl_add_u64 v[2:3], v[4:5], 0, s[0:1]
	s_add_u32 s0, s14, 0x2b0080
	s_mov_b32 m0, s66
	s_addc_u32 s1, s15, 0
	global_load_lds_dwordx4 v[2:3], off
	s_add_i32 m0, s58, 0x1c000
	v_lshl_add_u64 v[2:3], s[0:1], 0, v[142:143]
	global_load_lds_dwordx4 v[2:3], off
	v_lshl_add_u64 v[2:3], s[0:1], 0, v[146:147]
	s_add_i32 m0, s58, 0x1e000
	s_cmpk_lt_u32 s94, 0x100
	global_load_lds_dwordx4 v[2:3], off
	v_lshrrev_b32_e32 v3, 1, v10
	v_and_b32_e32 v3, 24, v3
	v_and_b32_e32 v2, 15, v10
	v_lshlrev_b32_e32 v4, 1, v3
	v_lshl_or_b32 v165, s6, 6, v2
	v_lshl_or_b32 v2, v2, 6, v4
	v_lshlrev_b32_e32 v4, 2, v10
	v_and_b32_e32 v4, 32, v4
	v_bitop3_b32 v5, v2, s8, v4 bitop3:0xde
	v_bitop3_b32 v166, v2, s9, v4 bitop3:0xde
	s_waitcnt vmcnt(6)
	s_cselect_b64 s[22:23], -1, 0
	s_or_b32 s6, s7, s6
	v_lshl_or_b32 v167, s7, 5, v3
	v_mov_b32_e32 v2, v0
	v_mov_b32_e32 v3, v0
	v_cndmask_b32_e64 v4, 0, 1, s[4:5]
	v_cmp_eq_u32_e64 s[0:1], 0, v1
	s_cmp_eq_u32 s6, 0
	v_mov_b32_e32 v1, v0
	v_cmp_ne_u32_e64 s[4:5], 1, v4
	v_add_u32_e32 v168, 0, v5
	s_cselect_b64 s[24:25], -1, 0
	s_add_i32 s67, 0, 0x10000
	s_add_i32 s72, 0, 0x14000
	v_mov_b64_e32 v[148:149], 0x3ff
	v_mov_b64_e32 v[150:151], 0x7f
	v_mov_b64_e32 v[152:153], 0x80
	v_mov_b64_e32 v[154:155], 0x3d0901
	s_barrier
	s_branch .LBB0_1321
.LBB0_1319:
	v_mov_b32_e32 v2, v0
	v_mov_b32_e32 v3, v0
	v_mov_b32_e32 v1, v0
	s_mov_b32 s56, s77
	s_mov_b32 s3, s74
	s_mov_b32 s54, s75
	s_mov_b32 s55, s76
	s_mov_b64 s[12:13], s[26:27]
	s_mov_b64 s[14:15], s[28:29]
	s_mov_b32 s64, s73

; #define PG8_STAGE(bufoff, gbase, voff) do { _Pragma("unroll") for (int _i = 0; _i < 2; ++_i) \
;         __builtin_amdgcn_global_load_lds((const unsigned*)((const char*)(gbase) + (voff)[_i]), (PG8_LAS unsigned*)(lds + (bufoff) + ldsw + _i * 8192), 16, 0, 0); } while (0)
; #define PG8_LDA(dst, b, h) do { _Pragma("unroll") for (int m = 0; m < 4; ++m) _Pragma("unroll") for (int k = 0; k < 2; ++k) dst[m][k] = *(const PG8_LAS bf16x8*)(lds + PG8_SA(b, h) + aoff + m * 2048 + k * 1024); } while (0)
; #define PG8_LDB(dst, b, h) do { _Pragma("unroll") for (int n = 0; n < 2; ++n) _Pragma("unroll") for (int k = 0; k < 2; ++k) dst[n][k] = *(const PG8_LAS bf16x8*)(lds + PG8_SB(b, h) + boff + n * 2048 + k * 1024); } while (0)
; #define PG8_WAIT_V(n) asm volatile("s_waitcnt vmcnt(" #n ")" ::: "memory")
; #define PG8_WAIT_L(n) asm volatile("s_waitcnt lgkmcnt(" #n ")" ::: "memory")
; #define PG8_BAR __builtin_amdgcn_s_barrier()
; #define PG8_SCHED __builtin_amdgcn_sched_barrier(0)
; template <class Epi, class Sched, bool ALIGN_EPI = false, bool SP2 = false, bool F8 = false>
; __device__ __forceinline__ void gemm_phase(PG8_LAS unsigned char* lds, const int K, const Sched& S, const Epi& E, const int wave) {
;     ...
;         const bool has_next = S.next(ui + 1, nxt);
;         const char* nA = has_next ? nxt.a : cA; const char* nB = has_next ? nxt.b : cB;
;         const int nt = cur.nt;
;         for (int t = 0; t < nt; t += 2) {
;             const bool last = (t == nt - 2);
;             const char* a1 = cA + (size_t)(t + 1) * kstep;
;             const char* a2 = last ? nA : cA + (size_t)(t + 2) * kstep; const char* b2 = last ? nB : cB + (size_t)(t + 2) * kstep;
;             const char* a3 = a2 + kstep; const char* b3 = b2 + kstep;
;             asm volatile("" : "+s"(a1), "+s"(a2), "+s"(b2), "+s"(a3), "+s"(b3));
;             if (last && has_next) S.a_ready(nxt);
;             if constexpr (Epi::KHOOK) { if (cur.prob == 2 ? (t == 16) : (t == 32 || t == 48)) { if (wr == 0) PG8_BAR;
;                 E.khook(acc, cur, (cur.prob == 2 || t == 48) ? 1 : 0, wr, wc, fr, fq); if (wr == 1) PG8_BAR; } }
;             if constexpr (SP2) {
;             PG8_LDB(B0, 0, 0); PG8_LDB(B1, 0, 1); PG8_SCHED; PG8_LDA(At, 0, 0); PG8_STAGE(PG8_SA(1, 1), a1 + hstep, voffA);
;             PG8_WAIT_V(8); PG8_WAIT_L(0); PG8_BAR; PG8_MMA(0, 0, At, B0); PG8_MMA(0, 1, At, B1); PG8_BAR; PG8_SCHED;
.LBB0_1346:
	s_xor_b64 s[30:31], s[36:37], -1
	s_cmp_lt_i32 s56, 1
	s_cbranch_scc1 .LBB0_1349
	s_and_b64 s[6:7], s[36:37], exec
	s_cselect_b32 s78, s27, s13
	s_cselect_b32 s79, s26, s12
	s_cselect_b32 s80, s29, s15
	s_cselect_b32 s81, s28, s14
	s_add_i32 s82, s56, -2
	s_add_u32 s83, s12, 0x100
	s_addc_u32 s84, s13, 0
	s_add_u32 s85, s14, 0x100
	s_addc_u32 s86, s15, 0
	s_add_u32 s6, s12, 0x80
	s_addc_u32 s7, s13, 0
	s_mov_b32 s8, 0
	s_add_i32 s87, s8, 2
	s_cmp_eq_u32 s82, s8
	s_cselect_b32 s40, s79, s83
	s_cselect_b32 s41, s78, s84
	s_cselect_b32 s43, s80, s86
	s_cselect_b32 s42, s81, s85
	s_add_u32 s8, s40, 0x80
	s_addc_u32 s9, s41, 0
	s_add_u32 s38, s42, 0x80
	s_addc_u32 s39, s43, 0
	s_mov_b64 s[88:89], s[6:7]
	v_add_u32_e32 v1, s67, v166
	ds_read_b128 v[132:135], v1
	ds_read_b128 v[136:139], v1 offset:1024
	ds_read_b128 v[156:159], v1 offset:2048
	ds_read_b128 v[160:163], v1 offset:3072
	v_add_u32_e32 v1, s72, v166
	ds_read_b128 v[170:173], v1
	ds_read_b128 v[174:177], v1 offset:1024
	ds_read_b128 v[178:181], v1 offset:2048
	ds_read_b128 v[182:185], v1 offset:3072
	s_add_u32 s88, s88, 0x2b0000
	s_addc_u32 s89, s89, 0
	v_lshl_add_u64 v[2:3], s[88:89], 0, v[140:141]
	s_add_i32 m0, s58, 0xc000
	ds_read_b128 v[186:189], v168
	ds_read_b128 v[190:193], v168 offset:1024
	ds_read_b128 v[194:197], v168 offset:2048
	ds_read_b128 v[198:201], v168 offset:3072
	ds_read_b128 v[202:205], v168 offset:4096
	ds_read_b128 v[206:209], v168 offset:5120
	ds_read_b128 v[210:213], v168 offset:6144
	ds_read_b128 v[214:217], v168 offset:7168
	global_load_lds_dwordx4 v[2:3], off
	v_lshl_add_u64 v[2:3], s[88:89], 0, v[144:145]
	s_add_i32 m0, s58, 0xe000
	s_nop 0
	global_load_lds_dwordx4 v[2:3], off
	s_waitcnt vmcnt(8)
	s_waitcnt lgkmcnt(0)
	s_setprio 1
	s_barrier
	v_mfma_f32_16x16x32_bf16 v[128:131], v[132:135], v[186:189], 0
	v_mfma_f32_16x16x32_bf16 v[124:127], v[156:159], v[186:189], 0
	v_mfma_f32_16x16x32_bf16 v[120:123], v[132:135], v[194:197], 0
	v_mfma_f32_16x16x32_bf16 v[116:119], v[156:159], v[194:197], 0
	v_mfma_f32_16x16x32_bf16 v[112:115], v[132:135], v[202:205], 0
	v_mfma_f32_16x16x32_bf16 v[108:111], v[156:159], v[202:205], 0
	v_mfma_f32_16x16x32_bf16 v[104:107], v[132:135], v[210:213], 0
	v_mfma_f32_16x16x32_bf16 v[100:103], v[156:159], v[210:213], 0
	v_mfma_f32_16x16x32_bf16 v[128:131], v[136:139], v[190:193], v[128:131]
	v_mfma_f32_16x16x32_bf16 v[124:127], v[160:163], v[190:193], v[124:127]
	v_mfma_f32_16x16x32_bf16 v[120:123], v[136:139], v[198:201], v[120:123]
	v_mfma_f32_16x16x32_bf16 v[116:119], v[160:163], v[198:201], v[116:119]
	v_mfma_f32_16x16x32_bf16 v[112:115], v[136:139], v[206:209], v[112:115]
	v_mfma_f32_16x16x32_bf16 v[108:111], v[160:163], v[206:209], v[108:111]
	v_mfma_f32_16x16x32_bf16 v[104:107], v[136:139], v[214:217], v[104:107]
	v_mfma_f32_16x16x32_bf16 v[100:103], v[160:163], v[214:217], v[100:103]
	v_mfma_f32_16x16x32_bf16 v[96:99], v[170:173], v[186:189], 0
	v_mfma_f32_16x16x32_bf16 v[92:95], v[178:181], v[186:189], 0
	v_mfma_f32_16x16x32_bf16 v[88:91], v[170:173], v[194:197], 0
	v_mfma_f32_16x16x32_bf16 v[84:87], v[178:181], v[194:197], 0
	v_mfma_f32_16x16x32_bf16 v[80:83], v[170:173], v[202:205], 0
	v_mfma_f32_16x16x32_bf16 v[76:79], v[178:181], v[202:205], 0
	v_mfma_f32_16x16x32_bf16 v[72:75], v[170:173], v[210:213], 0
	v_mfma_f32_16x16x32_bf16 v[68:71], v[178:181], v[210:213], 0
	v_mfma_f32_16x16x32_bf16 v[96:99], v[174:177], v[190:193], v[96:99]
	v_mfma_f32_16x16x32_bf16 v[92:95], v[182:185], v[190:193], v[92:95]
	v_mfma_f32_16x16x32_bf16 v[88:91], v[174:177], v[198:201], v[88:91]
	v_mfma_f32_16x16x32_bf16 v[84:87], v[182:185], v[198:201], v[84:87]
	v_mfma_f32_16x16x32_bf16 v[80:83], v[174:177], v[206:209], v[80:83]
	v_mfma_f32_16x16x32_bf16 v[76:79], v[182:185], v[206:209], v[76:79]
	v_mfma_f32_16x16x32_bf16 v[72:75], v[174:177], v[214:217], v[72:75]
	v_mfma_f32_16x16x32_bf16 v[68:71], v[182:185], v[214:217], v[68:71]
	s_barrier
; #define PG8_STAGE(bufoff, gbase, voff) do { _Pragma("unroll") for (int _i = 0; _i < 2; ++_i) \
;         __builtin_amdgcn_global_load_lds((const unsigned*)((const char*)(gbase) + (voff)[_i]), (PG8_LAS unsigned*)(lds + (bufoff) + ldsw + _i * 8192), 16, 0, 0); } while (0)
; #define PG8_LDA(dst, b, h) do { _Pragma("unroll") for (int m = 0; m < 4; ++m) _Pragma("unroll") for (int k = 0; k < 2; ++k) dst[m][k] = *(const PG8_LAS bf16x8*)(lds + PG8_SA(b, h) + aoff + m * 2048 + k * 1024); } while (0)
; #define PG8_WAIT_V(n) asm volatile("s_waitcnt vmcnt(" #n ")" ::: "memory")
; #define PG8_WAIT_L(n) asm volatile("s_waitcnt lgkmcnt(" #n ")" ::: "memory")
; #define PG8_BAR __builtin_amdgcn_s_barrier()
; #define PG8_SCHED __builtin_amdgcn_sched_barrier(0)
; template <class Epi, class Sched, bool ALIGN_EPI = false, bool SP2 = false, bool F8 = false>
; __device__ __forceinline__ void gemm_phase(PG8_LAS unsigned char* lds, const int K, const Sched& S, const Epi& E, const int wave) {
;     ...
;             PG8_LDA(At, 0, 1); PG8_STAGE(PG8_SB(0, 0), b2, voffB); PG8_STAGE(PG8_SB(0, 1), b2 + hstep, voffB); PG8_STAGE(PG8_SA(0, 0), a2, voffA);
;             PG8_WAIT_V(8); PG8_WAIT_L(0); PG8_BAR; PG8_MMA(1, 0, At, B0); PG8_MMA(1, 1, At, B1); PG8_BAR; PG8_SCHED;
	s_setprio 0
	s_add_i32 s88, s67, s57
	v_lshl_add_u64 v[2:3], s[42:43], 0, v[142:143]
	s_mov_b32 m0, s88
	ds_read_b128 v[186:189], v168 offset:16384
	ds_read_b128 v[190:193], v168 offset:17408
	ds_read_b128 v[194:197], v168 offset:18432
	ds_read_b128 v[198:201], v168 offset:19456
	ds_read_b128 v[202:205], v168 offset:20480
	ds_read_b128 v[206:209], v168 offset:21504
	ds_read_b128 v[210:213], v168 offset:22528
	ds_read_b128 v[214:217], v168 offset:23552
	global_load_lds_dwordx4 v[2:3], off
	s_add_i32 m0, s88, 0x2000
	v_lshl_add_u64 v[2:3], s[42:43], 0, v[146:147]
	s_add_u32 s42, s42, 0x2b0000
	s_addc_u32 s43, s43, 0
	s_add_i32 s88, s72, s57
	global_load_lds_dwordx4 v[2:3], off
	v_lshl_add_u64 v[2:3], s[42:43], 0, v[142:143]
	s_mov_b32 m0, s88
	s_nop 0
	global_load_lds_dwordx4 v[2:3], off
	v_lshl_add_u64 v[2:3], s[42:43], 0, v[146:147]
	s_add_i32 m0, s88, 0x2000
	s_nop 0
	global_load_lds_dwordx4 v[2:3], off
	v_lshl_add_u64 v[2:3], s[40:41], 0, v[140:141]
	s_mov_b32 m0, s58
	s_nop 0
	global_load_lds_dwordx4 v[2:3], off
	v_lshl_add_u64 v[2:3], s[40:41], 0, v[144:145]
	s_mov_b32 m0, s59
	s_nop 0
	global_load_lds_dwordx4 v[2:3], off
	s_waitcnt vmcnt(8)
	s_waitcnt lgkmcnt(0)
	s_setprio 1
	s_barrier
	v_mfma_f32_16x16x32_bf16 v[64:67], v[132:135], v[186:189], 0
	v_mfma_f32_16x16x32_bf16 v[60:63], v[156:159], v[186:189], 0
	v_mfma_f32_16x16x32_bf16 v[56:59], v[132:135], v[194:197], 0
	v_mfma_f32_16x16x32_bf16 v[52:55], v[156:159], v[194:197], 0
	v_mfma_f32_16x16x32_bf16 v[48:51], v[132:135], v[202:205], 0
	v_mfma_f32_16x16x32_bf16 v[44:47], v[156:159], v[202:205], 0
	v_mfma_f32_16x16x32_bf16 v[40:43], v[132:135], v[210:213], 0
	v_mfma_f32_16x16x32_bf16 v[36:39], v[156:159], v[210:213], 0
	v_mfma_f32_16x16x32_bf16 v[64:67], v[136:139], v[190:193], v[64:67]
	v_mfma_f32_16x16x32_bf16 v[60:63], v[160:163], v[190:193], v[60:63]
	v_mfma_f32_16x16x32_bf16 v[56:59], v[136:139], v[198:201], v[56:59]
	v_mfma_f32_16x16x32_bf16 v[52:55], v[160:163], v[198:201], v[52:55]
	v_mfma_f32_16x16x32_bf16 v[48:51], v[136:139], v[206:209], v[48:51]
	v_mfma_f32_16x16x32_bf16 v[44:47], v[160:163], v[206:209], v[44:47]
	v_mfma_f32_16x16x32_bf16 v[40:43], v[136:139], v[214:217], v[40:43]
	v_mfma_f32_16x16x32_bf16 v[36:39], v[160:163], v[214:217], v[36:39]
	v_mfma_f32_16x16x32_bf16 v[32:35], v[170:173], v[186:189], 0
	v_mfma_f32_16x16x32_bf16 v[28:31], v[178:181], v[186:189], 0
	v_mfma_f32_16x16x32_bf16 v[24:27], v[170:173], v[194:197], 0
	v_mfma_f32_16x16x32_bf16 v[20:23], v[178:181], v[194:197], 0
	v_mfma_f32_16x16x32_bf16 v[16:19], v[170:173], v[202:205], 0
	v_mfma_f32_16x16x32_bf16 v[12:15], v[178:181], v[202:205], 0
	v_mfma_f32_16x16x32_bf16 v[8:11], v[170:173], v[210:213], 0
	v_mfma_f32_16x16x32_bf16 v[2:5], v[178:181], v[210:213], 0
	v_mfma_f32_16x16x32_bf16 v[32:35], v[174:177], v[190:193], v[32:35]
	v_mfma_f32_16x16x32_bf16 v[28:31], v[182:185], v[190:193], v[28:31]
	v_mfma_f32_16x16x32_bf16 v[24:27], v[174:177], v[198:201], v[24:27]
	v_mfma_f32_16x16x32_bf16 v[20:23], v[182:185], v[198:201], v[20:23]
	v_mfma_f32_16x16x32_bf16 v[16:19], v[174:177], v[206:209], v[16:19]
	v_mfma_f32_16x16x32_bf16 v[12:15], v[182:185], v[206:209], v[12:15]
	v_mfma_f32_16x16x32_bf16 v[8:11], v[174:177], v[214:217], v[8:11]
	v_mfma_f32_16x16x32_bf16 v[2:5], v[182:185], v[214:217], v[2:5]
	s_barrier
	s_branch .Lmid_k1348

; #define PG8_STAGE(bufoff, gbase, voff) do { _Pragma("unroll") for (int _i = 0; _i < 2; ++_i) \
;         __builtin_amdgcn_global_load_lds((const unsigned*)((const char*)(gbase) + (voff)[_i]), (PG8_LAS unsigned*)(lds + (bufoff) + ldsw + _i * 8192), 16, 0, 0); } while (0)
; #define PG8_LDA(dst, b, h) do { _Pragma("unroll") for (int m = 0; m < 4; ++m) _Pragma("unroll") for (int k = 0; k < 2; ++k) dst[m][k] = *(const PG8_LAS bf16x8*)(lds + PG8_SA(b, h) + aoff + m * 2048 + k * 1024); } while (0)
; #define PG8_LDB(dst, b, h) do { _Pragma("unroll") for (int n = 0; n < 2; ++n) _Pragma("unroll") for (int k = 0; k < 2; ++k) dst[n][k] = *(const PG8_LAS bf16x8*)(lds + PG8_SB(b, h) + boff + n * 2048 + k * 1024); } while (0)
; #define PG8_WAIT_V(n) asm volatile("s_waitcnt vmcnt(" #n ")" ::: "memory")
; #define PG8_WAIT_L(n) asm volatile("s_waitcnt lgkmcnt(" #n ")" ::: "memory")
; #define PG8_BAR __builtin_amdgcn_s_barrier()
; #define PG8_SCHED __builtin_amdgcn_sched_barrier(0)
; template <class Epi, class Sched, bool ALIGN_EPI = false, bool SP2 = false, bool F8 = false>
; __device__ __forceinline__ void gemm_phase(PG8_LAS unsigned char* lds, const int K, const Sched& S, const Epi& E, const int wave) {
;     ...
;             PG8_LDB(B0, 1, 0); PG8_LDB(B1, 1, 1); PG8_SCHED; PG8_LDA(At, 1, 0); PG8_STAGE(PG8_SA(0, 1), a2 + hstep, voffA);
;             PG8_WAIT_V(8); PG8_WAIT_L(0); PG8_BAR; PG8_MMA(0, 0, At, B0); PG8_MMA(0, 1, At, B1); PG8_BAR; PG8_SCHED;
.Lmid_k1348:
	s_setprio 0
	s_add_i32 s42, 0, 0x18000
	v_add_u32_e32 v1, s42, v166
	s_add_i32 s43, 0, 0x1c000
	ds_read_b128 v[132:135], v1
	ds_read_b128 v[136:139], v1 offset:1024
	ds_read_b128 v[156:159], v1 offset:2048
	ds_read_b128 v[160:163], v1 offset:3072
	v_add_u32_e32 v1, s43, v166
	ds_read_b128 v[170:173], v1
	ds_read_b128 v[174:177], v1 offset:1024
	ds_read_b128 v[178:181], v1 offset:2048
	ds_read_b128 v[182:185], v1 offset:3072
	s_add_u32 s40, s40, 0x2b0000
	s_addc_u32 s41, s41, 0
	s_mov_b32 m0, s60
	v_lshl_add_u64 v[6:7], s[40:41], 0, v[140:141]
	ds_read_b128 v[186:189], v168 offset:32768
	ds_read_b128 v[190:193], v168 offset:33792
	ds_read_b128 v[194:197], v168 offset:34816
	ds_read_b128 v[198:201], v168 offset:35840
	ds_read_b128 v[202:205], v168 offset:36864
	ds_read_b128 v[206:209], v168 offset:37888
	ds_read_b128 v[210:213], v168 offset:38912
	ds_read_b128 v[214:217], v168 offset:39936
	global_load_lds_dwordx4 v[6:7], off
	v_lshl_add_u64 v[6:7], s[40:41], 0, v[144:145]
	s_mov_b32 m0, s61
	s_nop 0
	global_load_lds_dwordx4 v[6:7], off
	s_waitcnt vmcnt(8)
	s_waitcnt lgkmcnt(0)
	s_setprio 1
	s_barrier
	v_mfma_f32_16x16x32_bf16 v[128:131], v[132:135], v[186:189], v[128:131]
	v_mfma_f32_16x16x32_bf16 v[124:127], v[156:159], v[186:189], v[124:127]
	v_mfma_f32_16x16x32_bf16 v[120:123], v[132:135], v[194:197], v[120:123]
	v_mfma_f32_16x16x32_bf16 v[116:119], v[156:159], v[194:197], v[116:119]
	v_mfma_f32_16x16x32_bf16 v[112:115], v[132:135], v[202:205], v[112:115]
	v_mfma_f32_16x16x32_bf16 v[108:111], v[156:159], v[202:205], v[108:111]
	v_mfma_f32_16x16x32_bf16 v[104:107], v[132:135], v[210:213], v[104:107]
	v_mfma_f32_16x16x32_bf16 v[100:103], v[156:159], v[210:213], v[100:103]
	v_mfma_f32_16x16x32_bf16 v[128:131], v[136:139], v[190:193], v[128:131]
	v_mfma_f32_16x16x32_bf16 v[124:127], v[160:163], v[190:193], v[124:127]
	v_mfma_f32_16x16x32_bf16 v[120:123], v[136:139], v[198:201], v[120:123]
	v_mfma_f32_16x16x32_bf16 v[116:119], v[160:163], v[198:201], v[116:119]
	v_mfma_f32_16x16x32_bf16 v[112:115], v[136:139], v[206:209], v[112:115]
	v_mfma_f32_16x16x32_bf16 v[108:111], v[160:163], v[206:209], v[108:111]
	v_mfma_f32_16x16x32_bf16 v[104:107], v[136:139], v[214:217], v[104:107]
	v_mfma_f32_16x16x32_bf16 v[100:103], v[160:163], v[214:217], v[100:103]
	v_mfma_f32_16x16x32_bf16 v[96:99], v[170:173], v[186:189], v[96:99]
	v_mfma_f32_16x16x32_bf16 v[92:95], v[178:181], v[186:189], v[92:95]
	v_mfma_f32_16x16x32_bf16 v[88:91], v[170:173], v[194:197], v[88:91]
	v_mfma_f32_16x16x32_bf16 v[84:87], v[178:181], v[194:197], v[84:87]
	v_mfma_f32_16x16x32_bf16 v[80:83], v[170:173], v[202:205], v[80:83]
	v_mfma_f32_16x16x32_bf16 v[76:79], v[178:181], v[202:205], v[76:79]
	v_mfma_f32_16x16x32_bf16 v[72:75], v[170:173], v[210:213], v[72:75]
	v_mfma_f32_16x16x32_bf16 v[68:71], v[178:181], v[210:213], v[68:71]
	v_mfma_f32_16x16x32_bf16 v[96:99], v[174:177], v[190:193], v[96:99]
	v_mfma_f32_16x16x32_bf16 v[92:95], v[182:185], v[190:193], v[92:95]
	v_mfma_f32_16x16x32_bf16 v[88:91], v[174:177], v[198:201], v[88:91]
	v_mfma_f32_16x16x32_bf16 v[84:87], v[182:185], v[198:201], v[84:87]
	v_mfma_f32_16x16x32_bf16 v[80:83], v[174:177], v[206:209], v[80:83]
	v_mfma_f32_16x16x32_bf16 v[76:79], v[182:185], v[206:209], v[76:79]
	v_mfma_f32_16x16x32_bf16 v[72:75], v[174:177], v[214:217], v[72:75]
	v_mfma_f32_16x16x32_bf16 v[68:71], v[182:185], v[214:217], v[68:71]
	s_barrier
; #define PG8_STAGE(bufoff, gbase, voff) do { _Pragma("unroll") for (int _i = 0; _i < 2; ++_i) \
;         __builtin_amdgcn_global_load_lds((const unsigned*)((const char*)(gbase) + (voff)[_i]), (PG8_LAS unsigned*)(lds + (bufoff) + ldsw + _i * 8192), 16, 0, 0); } while (0)
; #define PG8_LDA(dst, b, h) do { _Pragma("unroll") for (int m = 0; m < 4; ++m) _Pragma("unroll") for (int k = 0; k < 2; ++k) dst[m][k] = *(const PG8_LAS bf16x8*)(lds + PG8_SA(b, h) + aoff + m * 2048 + k * 1024); } while (0)
; #define PG8_WAIT_V(n) asm volatile("s_waitcnt vmcnt(" #n ")" ::: "memory")
; #define PG8_WAIT_L(n) asm volatile("s_waitcnt lgkmcnt(" #n ")" ::: "memory")
; #define PG8_BAR __builtin_amdgcn_s_barrier()
; #define PG8_SCHED __builtin_amdgcn_sched_barrier(0)
; template <class Epi, class Sched, bool ALIGN_EPI = false, bool SP2 = false, bool F8 = false>
; __device__ __forceinline__ void gemm_phase(PG8_LAS unsigned char* lds, const int K, const Sched& S, const Epi& E, const int wave) {
;     ...
;             PG8_LDA(At, 1, 1); PG8_STAGE(PG8_SB(1, 0), b3, voffB); PG8_STAGE(PG8_SB(1, 1), b3 + hstep, voffB); PG8_STAGE(PG8_SA(1, 0), a3, voffA);
;             PG8_WAIT_V(8); PG8_WAIT_L(0); PG8_BAR; PG8_MMA(1, 0, At, B0); PG8_MMA(1, 1, At, B1); PG8_BAR; PG8_SCHED;
	s_setprio 0
	s_add_i32 s40, s42, s57
	v_lshl_add_u64 v[6:7], s[38:39], 0, v[142:143]
	s_mov_b32 m0, s40
	ds_read_b128 v[186:189], v168 offset:49152
	ds_read_b128 v[190:193], v168 offset:50176
	ds_read_b128 v[194:197], v168 offset:51200
	ds_read_b128 v[198:201], v168 offset:52224
	ds_read_b128 v[202:205], v168 offset:53248
	ds_read_b128 v[206:209], v168 offset:54272
	ds_read_b128 v[210:213], v168 offset:55296
	ds_read_b128 v[214:217], v168 offset:56320
	global_load_lds_dwordx4 v[6:7], off
	s_add_i32 m0, s40, 0x2000
	v_lshl_add_u64 v[6:7], s[38:39], 0, v[146:147]
	s_add_u32 s38, s38, 0x2b0000
	s_addc_u32 s39, s39, 0
	s_add_i32 s40, s43, s57
	global_load_lds_dwordx4 v[6:7], off
	v_lshl_add_u64 v[6:7], s[38:39], 0, v[142:143]
	s_mov_b32 m0, s40
	s_nop 0
	global_load_lds_dwordx4 v[6:7], off
	v_lshl_add_u64 v[6:7], s[38:39], 0, v[146:147]
	s_add_i32 m0, s40, 0x2000
	s_nop 0
	global_load_lds_dwordx4 v[6:7], off
	v_lshl_add_u64 v[6:7], s[8:9], 0, v[140:141]
	s_mov_b32 m0, s65
	s_nop 0
	global_load_lds_dwordx4 v[6:7], off
	v_lshl_add_u64 v[6:7], s[8:9], 0, v[144:145]
	s_mov_b32 m0, s66
	s_nop 0
	global_load_lds_dwordx4 v[6:7], off
	s_waitcnt vmcnt(8)
	s_waitcnt lgkmcnt(0)
	s_setprio 1
	s_barrier
	v_mfma_f32_16x16x32_bf16 v[64:67], v[132:135], v[186:189], v[64:67]
	v_mfma_f32_16x16x32_bf16 v[60:63], v[156:159], v[186:189], v[60:63]
	v_mfma_f32_16x16x32_bf16 v[56:59], v[132:135], v[194:197], v[56:59]
	v_mfma_f32_16x16x32_bf16 v[52:55], v[156:159], v[194:197], v[52:55]
	v_mfma_f32_16x16x32_bf16 v[48:51], v[132:135], v[202:205], v[48:51]
	v_mfma_f32_16x16x32_bf16 v[44:47], v[156:159], v[202:205], v[44:47]
	v_mfma_f32_16x16x32_bf16 v[40:43], v[132:135], v[210:213], v[40:43]
	v_mfma_f32_16x16x32_bf16 v[36:39], v[156:159], v[210:213], v[36:39]
	v_mfma_f32_16x16x32_bf16 v[64:67], v[136:139], v[190:193], v[64:67]
	v_mfma_f32_16x16x32_bf16 v[60:63], v[160:163], v[190:193], v[60:63]
	v_mfma_f32_16x16x32_bf16 v[56:59], v[136:139], v[198:201], v[56:59]
	v_mfma_f32_16x16x32_bf16 v[52:55], v[160:163], v[198:201], v[52:55]
	v_mfma_f32_16x16x32_bf16 v[48:51], v[136:139], v[206:209], v[48:51]
	v_mfma_f32_16x16x32_bf16 v[44:47], v[160:163], v[206:209], v[44:47]
	v_mfma_f32_16x16x32_bf16 v[40:43], v[136:139], v[214:217], v[40:43]
	v_mfma_f32_16x16x32_bf16 v[36:39], v[160:163], v[214:217], v[36:39]
	v_mfma_f32_16x16x32_bf16 v[32:35], v[170:173], v[186:189], v[32:35]
	v_mfma_f32_16x16x32_bf16 v[28:31], v[178:181], v[186:189], v[28:31]
	v_mfma_f32_16x16x32_bf16 v[24:27], v[170:173], v[194:197], v[24:27]
	v_mfma_f32_16x16x32_bf16 v[20:23], v[178:181], v[194:197], v[20:23]
	v_mfma_f32_16x16x32_bf16 v[16:19], v[170:173], v[202:205], v[16:19]
	v_mfma_f32_16x16x32_bf16 v[12:15], v[178:181], v[202:205], v[12:15]
	v_mfma_f32_16x16x32_bf16 v[6:9], v[170:173], v[210:213], v[8:11]
	v_mfma_f32_16x16x32_bf16 v[2:5], v[178:181], v[210:213], v[2:5]
	v_mfma_f32_16x16x32_bf16 v[32:35], v[174:177], v[190:193], v[32:35]
	v_mfma_f32_16x16x32_bf16 v[28:31], v[182:185], v[190:193], v[28:31]
	v_mfma_f32_16x16x32_bf16 v[24:27], v[174:177], v[198:201], v[24:27]
	v_mfma_f32_16x16x32_bf16 v[20:23], v[182:185], v[198:201], v[20:23]
	v_mfma_f32_16x16x32_bf16 v[16:19], v[174:177], v[206:209], v[16:19]
	v_mfma_f32_16x16x32_bf16 v[12:15], v[182:185], v[206:209], v[12:15]
	v_mfma_f32_16x16x32_bf16 v[8:11], v[174:177], v[214:217], v[6:9]
	v_mfma_f32_16x16x32_bf16 v[4:7], v[182:185], v[214:217], v[2:5]
	s_barrier
	s_setprio 0
	s_add_u32 s83, s83, 0x100
	s_addc_u32 s84, s84, 0
	s_add_u32 s85, s85, 0x100
	s_addc_u32 s86, s86, 0
	s_add_u32 s6, s6, 0x100
	s_addc_u32 s7, s7, 0
	s_cmp_ge_i32 s87, s56
	s_mov_b32 s8, s87
	s_cbranch_scc0 .LBB0_1348
